# FoX tile: mask-free fast path for non-diagonal tiles (on top of stack)
# baseline (speedup 1.0000x reference)
.LBB0_957:
	s_and_b32 s82, s52, 1
	s_cmp_gt_i32 s79, s76
	s_cselect_b64 s[50:51], -1, 0
	s_or_b64 s[50:51], s[50:51], s[20:21]
	s_and_b64 vcc, exec, s[50:51]
	s_cbranch_vccnz .LBB0_963
	s_add_i32 s20, s78, s77
	s_cmp_gt_i32 s20, s73
	s_cbranch_scc1 .Lfox_mask_F0
	s_mul_i32 s20, s82, 0xaa00
	s_add_i32 s52, s20, 0
	v_add_u32_e32 v199, s52, v179
	v_add_u32_e32 v1, v199, v180
	ds_read_b128 v[2:5], v1
	ds_read_b128 v[6:9], v1 offset:32
	v_add_u32_e32 v200, s78, v196
	s_add_i32 s20, s78, s77
	s_cmp_gt_i32 s20, s73
	s_waitcnt lgkmcnt(1)
	v_mfma_f32_32x32x16_bf16 v[96:111], v[2:5], v[112:115], 0
	ds_read_b128 v[2:5], v1 offset:4608
	ds_read_b128 v[10:13], v1 offset:4640
	s_cselect_b64 s[50:51], -1, 0
	s_waitcnt lgkmcnt(2)
	v_mfma_f32_32x32x16_bf16 v[96:111], v[6:9], v[116:119], v[96:111]
	s_waitcnt lgkmcnt(1)
	v_mfma_f32_32x32x16_bf16 v[80:95], v[2:5], v[112:115], 0
	ds_read_b128 v[2:5], v199 offset:43008
	ds_read_b128 v[202:205], v199 offset:43040
	ds_read_b128 v[48:51], v1 offset:64
	ds_read_b128 v[6:9], v1 offset:9216
	ds_read_b128 v[206:209], v1 offset:9248
	ds_read_b128 v[52:55], v1 offset:13824
	ds_read_b128 v[210:213], v1 offset:13856
	ds_read_b128 v[56:59], v1 offset:96
	ds_read_b128 v[214:217], v1 offset:4672
	ds_read_b128 v[218:221], v1 offset:4704
	ds_read_b128 v[222:225], v1 offset:9280
	ds_read_b128 v[226:229], v1 offset:9312
	ds_read_b128 v[230:233], v1 offset:13888
	ds_read_b128 v[238:241], v1 offset:13920
	s_waitcnt lgkmcnt(13)
	v_sub_f32_e32 v1, v163, v2
	s_waitcnt lgkmcnt(11)
	v_mfma_f32_32x32x16_bf16 v[96:111], v[48:51], v[120:123], v[96:111]
	v_sub_f32_e32 v2, v163, v3
	v_sub_f32_e32 v3, v163, v4
	s_waitcnt lgkmcnt(6)
	v_mfma_f32_32x32x16_bf16 v[96:111], v[56:59], v[124:127], v[96:111]
	v_mfma_f32_32x32x16_bf16 v[64:79], v[6:9], v[112:115], 0
	s_nop 10
	v_fmac_f32_e32 v1, 0x3e38aa3b, v96
	v_fmac_f32_e32 v2, 0x3e38aa3b, v97
	v_fmac_f32_e32 v3, 0x3e38aa3b, v98
	v_sub_f32_e32 v4, v163, v5
	v_fmac_f32_e32 v4, 0x3e38aa3b, v99
	v_sub_f32_e32 v6, v163, v202
	v_fmac_f32_e32 v6, 0x3e38aa3b, v100
	v_mov_b32_e32 v5, v6
	v_sub_f32_e32 v6, v163, v203
	v_mfma_f32_32x32x16_bf16 v[80:95], v[10:13], v[116:119], v[80:95]
	v_fmac_f32_e32 v6, 0x3e38aa3b, v101
	ds_read_b128 v[10:13], v199 offset:43072
	ds_read_b128 v[96:99], v199 offset:43104
	v_sub_f32_e32 v7, v163, v204
	v_fmac_f32_e32 v7, 0x3e38aa3b, v102
	v_sub_f32_e32 v8, v163, v205
	v_fmac_f32_e32 v8, 0x3e38aa3b, v103
	s_waitcnt lgkmcnt(1)
	v_sub_f32_e32 v10, v163, v10
	v_fmac_f32_e32 v10, 0x3e38aa3b, v104
	v_mov_b32_e32 v9, v10
	v_sub_f32_e32 v10, v163, v11
	v_mfma_f32_32x32x16_bf16 v[80:95], v[214:217], v[120:123], v[80:95]
	v_fmac_f32_e32 v10, 0x3e38aa3b, v105
	v_sub_f32_e32 v11, v163, v12
	v_fmac_f32_e32 v11, 0x3e38aa3b, v106
	v_sub_f32_e32 v12, v163, v13
	v_fmac_f32_e32 v12, 0x3e38aa3b, v107
	s_waitcnt lgkmcnt(0)
	v_sub_f32_e32 v14, v163, v96
	v_fmac_f32_e32 v14, 0x3e38aa3b, v108
	v_mfma_f32_32x32x16_bf16 v[80:95], v[218:221], v[124:127], v[80:95]
	v_mov_b32_e32 v13, v14
	v_sub_f32_e32 v14, v163, v97
	v_fmac_f32_e32 v14, 0x3e38aa3b, v109
	v_sub_f32_e32 v15, v163, v98
	v_sub_f32_e32 v96, v163, v99
	ds_read_b128 v[98:101], v199 offset:43136
	ds_read_b128 v[102:105], v199 offset:43168
	v_fmac_f32_e32 v15, 0x3e38aa3b, v110
	v_fmac_f32_e32 v96, 0x3e38aa3b, v111
	s_waitcnt lgkmcnt(1)
	v_sub_f32_e32 v98, v163, v98
	v_sub_f32_e32 v97, v163, v99
	v_fmac_f32_e32 v98, 0x3e38aa3b, v80
	v_fmac_f32_e32 v97, 0x3e38aa3b, v81
	v_mov_b32_e32 v80, v98
	s_waitcnt lgkmcnt(0)
	v_sub_f32_e32 v98, v163, v102
	v_mov_b32_e32 v81, v97
	v_sub_f32_e32 v97, v163, v100
	v_fmac_f32_e32 v97, 0x3e38aa3b, v82
	v_fmac_f32_e32 v98, 0x3e38aa3b, v84
	v_mov_b32_e32 v82, v97
	v_sub_f32_e32 v97, v163, v101
	v_fmac_f32_e32 v97, 0x3e38aa3b, v83
	v_mfma_f32_32x32x16_bf16 v[64:79], v[206:209], v[116:119], v[64:79]
	v_mov_b32_e32 v83, v97
	v_sub_f32_e32 v97, v163, v103
	v_fmac_f32_e32 v97, 0x3e38aa3b, v85
	v_mov_b32_e32 v84, v98
	ds_read_b128 v[98:101], v199 offset:43200
	v_mov_b32_e32 v85, v97
	v_sub_f32_e32 v97, v163, v104
	v_fmac_f32_e32 v97, 0x3e38aa3b, v86
	v_mfma_f32_32x32x16_bf16 v[64:79], v[222:225], v[120:123], v[64:79]
	v_mov_b32_e32 v86, v97
	v_sub_f32_e32 v97, v163, v105
	v_fmac_f32_e32 v97, 0x3e38aa3b, v87
	ds_read_b128 v[102:105], v199 offset:43232
	v_mov_b32_e32 v87, v97
	s_waitcnt lgkmcnt(1)
	v_sub_f32_e32 v98, v163, v98
	v_fmac_f32_e32 v98, 0x3e38aa3b, v88
	v_sub_f32_e32 v88, v163, v99
	v_fmac_f32_e32 v88, 0x3e38aa3b, v89
	v_mov_b32_e32 v97, v98
	v_mov_b32_e32 v98, v88
	v_sub_f32_e32 v88, v163, v100
	v_fmac_f32_e32 v88, 0x3e38aa3b, v90
	v_mov_b32_e32 v99, v88
	v_sub_f32_e32 v88, v163, v101
	v_fmac_f32_e32 v88, 0x3e38aa3b, v91
	v_mov_b32_e32 v100, v88
	s_waitcnt lgkmcnt(0)
	v_sub_f32_e32 v89, v163, v102
	v_fmac_f32_e32 v89, 0x3e38aa3b, v92
	v_mov_b32_e32 v101, v89
	v_sub_f32_e32 v88, v163, v103
	v_fmac_f32_e32 v88, 0x3e38aa3b, v93
	v_mfma_f32_32x32x16_bf16 v[64:79], v[226:229], v[124:127], v[64:79]
	v_mov_b32_e32 v102, v88
	v_sub_f32_e32 v88, v163, v104
	v_fmac_f32_e32 v88, 0x3e38aa3b, v94
	v_mov_b32_e32 v103, v88
	v_sub_f32_e32 v88, v163, v105
	ds_read_b128 v[104:107], v199 offset:43264
	ds_read_b128 v[108:111], v199 offset:43296
	v_fmac_f32_e32 v88, 0x3e38aa3b, v95
	s_waitcnt lgkmcnt(1)
	v_sub_f32_e32 v90, v163, v104
	s_nop 1
	v_fmac_f32_e32 v90, 0x3e38aa3b, v64
	v_sub_f32_e32 v64, v163, v105
	v_fmac_f32_e32 v64, 0x3e38aa3b, v65
	v_mov_b32_e32 v94, v90
	v_mov_b32_e32 v92, v64
	v_sub_f32_e32 v64, v163, v106
	v_fmac_f32_e32 v64, 0x3e38aa3b, v66
	v_mov_b32_e32 v93, v64
	v_sub_f32_e32 v64, v163, v107
	v_fmac_f32_e32 v64, 0x3e38aa3b, v67
	v_mov_b32_e32 v91, v64
	s_waitcnt lgkmcnt(0)
	v_sub_f32_e32 v65, v163, v108
	v_fmac_f32_e32 v65, 0x3e38aa3b, v68
	v_mov_b32_e32 v89, v65
	v_sub_f32_e32 v64, v163, v109
	v_mfma_f32_32x32x16_bf16 v[48:63], v[52:55], v[112:115], 0
	v_fmac_f32_e32 v64, 0x3e38aa3b, v69
	v_mov_b32_e32 v90, v64
	v_sub_f32_e32 v64, v163, v110
	v_fmac_f32_e32 v64, 0x3e38aa3b, v70
	v_mov_b32_e32 v67, v64
	v_sub_f32_e32 v64, v163, v111
	v_fmac_f32_e32 v64, 0x3e38aa3b, v71
	ds_read_b128 v[68:71], v199 offset:43328
	ds_read_b128 v[104:107], v199 offset:43360
	v_mfma_f32_32x32x16_bf16 v[48:63], v[210:213], v[116:119], v[48:63]
	s_waitcnt lgkmcnt(1)
	v_sub_f32_e32 v66, v163, v68
	v_fmac_f32_e32 v66, 0x3e38aa3b, v72
	v_mov_b32_e32 v72, v66
	v_sub_f32_e32 v65, v163, v69
	v_fmac_f32_e32 v65, 0x3e38aa3b, v73
	v_mov_b32_e32 v66, v65
	v_sub_f32_e32 v65, v163, v70
	v_fmac_f32_e32 v65, 0x3e38aa3b, v74
	v_mfma_f32_32x32x16_bf16 v[48:63], v[230:233], v[120:123], v[48:63]
	v_mov_b32_e32 v68, v65
	v_sub_f32_e32 v65, v163, v71
	v_fmac_f32_e32 v65, 0x3e38aa3b, v75
	v_mov_b32_e32 v71, v65
	s_waitcnt lgkmcnt(0)
	v_sub_f32_e32 v69, v163, v104
	v_fmac_f32_e32 v69, 0x3e38aa3b, v76
	v_mov_b32_e32 v73, v69
	v_sub_f32_e32 v65, v163, v105
	v_fmac_f32_e32 v65, 0x3e38aa3b, v77
	v_mfma_f32_32x32x16_bf16 v[48:63], v[238:241], v[124:127], v[48:63]
	v_mov_b32_e32 v70, v65
	v_sub_f32_e32 v65, v163, v106
	v_fmac_f32_e32 v65, 0x3e38aa3b, v78
	ds_read_b128 v[74:77], v199 offset:43392
	v_sub_f32_e32 v69, v163, v107
	v_fmac_f32_e32 v69, 0x3e38aa3b, v79
	ds_read_b128 v[104:107], v199 offset:43424
	s_waitcnt lgkmcnt(1)
	v_sub_f32_e32 v74, v163, v74
	s_nop 2
	v_fmac_f32_e32 v74, 0x3e38aa3b, v48
	v_sub_f32_e32 v48, v163, v75
	v_fmac_f32_e32 v48, 0x3e38aa3b, v49
	v_mov_b32_e32 v75, v48
	v_sub_f32_e32 v48, v163, v76
	v_fmac_f32_e32 v48, 0x3e38aa3b, v50
	v_mov_b32_e32 v76, v48
	v_sub_f32_e32 v48, v163, v77
	v_fmac_f32_e32 v48, 0x3e38aa3b, v51
	v_mov_b32_e32 v50, v48
	s_waitcnt lgkmcnt(0)
	v_sub_f32_e32 v49, v163, v104
	v_fmac_f32_e32 v49, 0x3e38aa3b, v52
	v_mov_b32_e32 v48, v49
	v_sub_f32_e32 v49, v163, v105
	v_fmac_f32_e32 v49, 0x3e38aa3b, v53
	v_sub_f32_e32 v51, v163, v106
	v_sub_f32_e32 v52, v163, v107
	ds_read_b128 v[104:107], v199 offset:43456
	ds_read_b128 v[108:111], v199 offset:43488
	v_fmac_f32_e32 v51, 0x3e38aa3b, v54
	v_fmac_f32_e32 v52, 0x3e38aa3b, v55
	s_waitcnt lgkmcnt(1)
	v_sub_f32_e32 v54, v163, v104
	v_fmac_f32_e32 v54, 0x3e38aa3b, v56
	v_mov_b32_e32 v77, v54
	v_sub_f32_e32 v53, v163, v105
	v_fmac_f32_e32 v53, 0x3e38aa3b, v57
	v_mov_b32_e32 v56, v53
	v_sub_f32_e32 v53, v163, v106
	v_fmac_f32_e32 v53, 0x3e38aa3b, v58
	v_sub_f32_e32 v54, v163, v107
	v_fmac_f32_e32 v54, 0x3e38aa3b, v59
	s_waitcnt lgkmcnt(0)
	v_sub_f32_e32 v57, v163, v108
	v_fmac_f32_e32 v57, 0x3e38aa3b, v60
	v_mov_b32_e32 v55, v57
	v_sub_f32_e32 v57, v163, v109
	v_fmac_f32_e32 v57, 0x3e38aa3b, v61
	v_mov_b32_e32 v58, v57
	v_sub_f32_e32 v57, v163, v110
	v_fmac_f32_e32 v57, 0x3e38aa3b, v62
	v_max_f32_e32 v62, v92, v75
	v_mov_b32_e32 v59, v57
	v_max_f32_e32 v60, v1, v80
	v_max_f32_e32 v61, v94, v74
	v_max3_f32 v62, v2, v81, v62
	v_max3_f32 v60, v60, v61, v62
	v_max_f32_e32 v61, v93, v76
	v_max_f32_e32 v62, v91, v50
	v_max3_f32 v61, v3, v82, v61
	v_max3_f32 v62, v4, v83, v62
	v_max3_f32 v60, v60, v61, v62
	v_max_f32_e32 v61, v89, v48
	v_max_f32_e32 v62, v90, v49
	v_max3_f32 v61, v5, v84, v61
	v_max3_f32 v62, v6, v85, v62
	v_max3_f32 v60, v60, v61, v62
	v_max_f32_e32 v61, v67, v51
	v_max_f32_e32 v62, v64, v52
	v_max3_f32 v61, v7, v86, v61
	v_max3_f32 v62, v8, v87, v62
	v_max3_f32 v60, v60, v61, v62
	v_max_f32_e32 v61, v72, v77
	v_max_f32_e32 v62, v66, v56
	v_max3_f32 v61, v9, v97, v61
	v_max3_f32 v62, v10, v98, v62
	v_max3_f32 v60, v60, v61, v62
	v_max_f32_e32 v61, v68, v53
	v_max_f32_e32 v62, v71, v54
	v_sub_f32_e32 v57, v163, v111
	v_max3_f32 v61, v11, v99, v61
	v_max3_f32 v62, v12, v100, v62
	v_fmac_f32_e32 v57, 0x3e38aa3b, v63
	v_max3_f32 v60, v60, v61, v62
	v_max_f32_e32 v61, v73, v55
	v_max_f32_e32 v62, v70, v58
	v_max3_f32 v61, v13, v101, v61
	v_max3_f32 v62, v14, v102, v62
	v_max3_f32 v60, v60, v61, v62
	v_max_f32_e32 v61, v65, v59
	v_max_f32_e32 v62, v69, v57
	v_max3_f32 v61, v15, v103, v61
	v_max3_f32 v62, v96, v88, v62
	v_max3_f32 v60, v60, v61, v62
	v_mov_b32_e32 v61, v60
	s_nop 1
	v_permlane32_swap_b32 v61, v60
	s_nop 1
	s_nop 0
	v_max_f32_e32 v60, v60, v60
	v_max_f32_e32 v61, v61, v61
	v_max_f32_e32 v60, v61, v60
	v_cmp_lt_f32_e32 vcc, s62, v60
	s_or_b64 s[20:21], s[24:25], vcc
	v_cndmask_b32_e64 v61, 0, 1, s[20:21]
	v_cmp_ne_u32_e32 vcc, 0, v61
	s_branch .Lfox_join_F0
.Lfox_mask_F0:
	s_mul_i32 s20, s82, 0xaa00
	s_add_i32 s52, s20, 0
	v_add_u32_e32 v199, s52, v179
	v_add_u32_e32 v1, v199, v180
	ds_read_b128 v[2:5], v1
	ds_read_b128 v[6:9], v1 offset:32
	v_add_u32_e32 v200, s78, v196
	s_add_i32 s20, s78, s77
	s_cmp_gt_i32 s20, s73
	s_waitcnt lgkmcnt(1)
	v_mfma_f32_32x32x16_bf16 v[96:111], v[2:5], v[112:115], 0
	ds_read_b128 v[2:5], v1 offset:4608
	ds_read_b128 v[10:13], v1 offset:4640
	s_cselect_b64 s[50:51], -1, 0
	v_add_u32_e32 v15, 0xffffff99, v200
	s_waitcnt lgkmcnt(2)
	v_mfma_f32_32x32x16_bf16 v[96:111], v[6:9], v[116:119], v[96:111]
	s_waitcnt lgkmcnt(1)
	v_mfma_f32_32x32x16_bf16 v[80:95], v[2:5], v[112:115], 0
	v_add_u32_e32 v2, 0xffffff80, v200
	v_cmp_gt_i32_e32 vcc, v2, v166
	v_cmp_ge_i32_e64 s[20:21], v2, v166
	ds_read_b128 v[2:5], v199 offset:43008
	ds_read_b128 v[202:205], v199 offset:43040
	ds_read_b128 v[48:51], v1 offset:64
	ds_read_b128 v[6:9], v1 offset:9216
	ds_read_b128 v[206:209], v1 offset:9248
	ds_read_b128 v[52:55], v1 offset:13824
	ds_read_b128 v[210:213], v1 offset:13856
	ds_read_b128 v[56:59], v1 offset:96
	ds_read_b128 v[214:217], v1 offset:4672
	ds_read_b128 v[218:221], v1 offset:4704
	ds_read_b128 v[222:225], v1 offset:9280
	ds_read_b128 v[226:229], v1 offset:9312
	ds_read_b128 v[230:233], v1 offset:13888
	ds_read_b128 v[238:241], v1 offset:13920
	s_waitcnt lgkmcnt(13)
	v_sub_f32_e32 v1, v163, v2
	s_waitcnt lgkmcnt(11)
	v_mfma_f32_32x32x16_bf16 v[96:111], v[48:51], v[120:123], v[96:111]
	v_sub_f32_e32 v2, v163, v3
	s_and_b64 vcc, s[50:51], vcc
	v_sub_f32_e32 v3, v163, v4
	v_add_u32_e32 v4, 0xffffff82, v200
	s_waitcnt lgkmcnt(6)
	v_mfma_f32_32x32x16_bf16 v[96:111], v[56:59], v[124:127], v[96:111]
	v_mfma_f32_32x32x16_bf16 v[64:79], v[6:9], v[112:115], 0
	s_nop 10
	v_fmac_f32_e32 v1, 0x3e38aa3b, v96
	v_fmac_f32_e32 v2, 0x3e38aa3b, v97
	v_cndmask_b32_e32 v1, v1, v192, vcc
	s_and_b64 vcc, s[50:51], s[20:21]
	v_cndmask_b32_e32 v2, v2, v192, vcc
	v_cmp_gt_i32_e32 vcc, v4, v166
	v_fmac_f32_e32 v3, 0x3e38aa3b, v98
	s_and_b64 vcc, s[50:51], vcc
	v_sub_f32_e32 v4, v163, v5
	v_add_u32_e32 v5, 0xffffff83, v200
	v_cndmask_b32_e32 v3, v3, v192, vcc
	v_cmp_gt_i32_e32 vcc, v5, v166
	v_fmac_f32_e32 v4, 0x3e38aa3b, v99
	s_and_b64 vcc, s[50:51], vcc
	v_add_u32_e32 v5, 0xffffff88, v200
	v_cndmask_b32_e32 v4, v4, v192, vcc
	v_sub_f32_e32 v6, v163, v202
	v_cmp_gt_i32_e32 vcc, v5, v166
	v_fmac_f32_e32 v6, 0x3e38aa3b, v100
	s_and_b64 vcc, s[50:51], vcc
	v_add_u32_e32 v7, 0xffffff89, v200
	v_cndmask_b32_e32 v5, v6, v192, vcc
	v_sub_f32_e32 v6, v163, v203
	v_cmp_gt_i32_e32 vcc, v7, v166
	v_mfma_f32_32x32x16_bf16 v[80:95], v[10:13], v[116:119], v[80:95]
	v_fmac_f32_e32 v6, 0x3e38aa3b, v101
	s_and_b64 vcc, s[50:51], vcc
	v_add_u32_e32 v8, 0xffffff8a, v200
	ds_read_b128 v[10:13], v199 offset:43072
	ds_read_b128 v[96:99], v199 offset:43104
	v_cndmask_b32_e32 v6, v6, v192, vcc
	v_sub_f32_e32 v7, v163, v204
	v_cmp_gt_i32_e32 vcc, v8, v166
	v_fmac_f32_e32 v7, 0x3e38aa3b, v102
	s_and_b64 vcc, s[50:51], vcc
	v_add_u32_e32 v9, 0xffffff8b, v200
	v_cndmask_b32_e32 v7, v7, v192, vcc
	v_sub_f32_e32 v8, v163, v205
	v_cmp_gt_i32_e32 vcc, v9, v166
	v_fmac_f32_e32 v8, 0x3e38aa3b, v103
	s_and_b64 vcc, s[50:51], vcc
	v_add_u32_e32 v9, 0xffffff90, v200
	v_cndmask_b32_e32 v8, v8, v192, vcc
	s_waitcnt lgkmcnt(1)
	v_sub_f32_e32 v10, v163, v10
	v_cmp_gt_i32_e32 vcc, v9, v166
	v_fmac_f32_e32 v10, 0x3e38aa3b, v104
	s_and_b64 vcc, s[50:51], vcc
	v_cndmask_b32_e32 v9, v10, v192, vcc
	v_sub_f32_e32 v10, v163, v11
	v_add_u32_e32 v11, 0xffffff91, v200
	v_mfma_f32_32x32x16_bf16 v[80:95], v[214:217], v[120:123], v[80:95]
	v_cmp_gt_i32_e32 vcc, v11, v166
	v_fmac_f32_e32 v10, 0x3e38aa3b, v105
	s_and_b64 vcc, s[50:51], vcc
	v_sub_f32_e32 v11, v163, v12
	v_add_u32_e32 v12, 0xffffff92, v200
	v_cndmask_b32_e32 v10, v10, v192, vcc
	v_cmp_gt_i32_e32 vcc, v12, v166
	v_fmac_f32_e32 v11, 0x3e38aa3b, v106
	s_and_b64 vcc, s[50:51], vcc
	v_sub_f32_e32 v12, v163, v13
	v_add_u32_e32 v13, 0xffffff93, v200
	v_cndmask_b32_e32 v11, v11, v192, vcc
	v_cmp_gt_i32_e32 vcc, v13, v166
	v_fmac_f32_e32 v12, 0x3e38aa3b, v107
	s_and_b64 vcc, s[50:51], vcc
	v_add_u32_e32 v13, 0xffffff98, v200
	v_cndmask_b32_e32 v12, v12, v192, vcc
	s_waitcnt lgkmcnt(0)
	v_sub_f32_e32 v14, v163, v96
	v_cmp_gt_i32_e32 vcc, v13, v166
	v_fmac_f32_e32 v14, 0x3e38aa3b, v108
	s_and_b64 vcc, s[50:51], vcc
	v_mfma_f32_32x32x16_bf16 v[80:95], v[218:221], v[124:127], v[80:95]
	v_cndmask_b32_e32 v13, v14, v192, vcc
	v_sub_f32_e32 v14, v163, v97
	v_cmp_gt_i32_e32 vcc, v15, v166
	v_fmac_f32_e32 v14, 0x3e38aa3b, v109
	s_and_b64 vcc, s[50:51], vcc
	v_add_u32_e32 v96, 0xffffff9a, v200
	v_cndmask_b32_e32 v14, v14, v192, vcc
	v_sub_f32_e32 v15, v163, v98
	v_cmp_gt_i32_e32 vcc, v96, v166
	v_sub_f32_e32 v96, v163, v99
	ds_read_b128 v[98:101], v199 offset:43136
	ds_read_b128 v[102:105], v199 offset:43168
	v_fmac_f32_e32 v15, 0x3e38aa3b, v110
	s_and_b64 vcc, s[50:51], vcc
	v_add_u32_e32 v97, 0xffffff9b, v200
	v_cndmask_b32_e32 v15, v15, v192, vcc
	v_cmp_gt_i32_e32 vcc, v97, v166
	v_fmac_f32_e32 v96, 0x3e38aa3b, v111
	s_and_b64 vcc, s[50:51], vcc
	v_add_u32_e32 v97, 0xffffffa0, v200
	v_cndmask_b32_e32 v96, v96, v192, vcc
	s_waitcnt lgkmcnt(1)
	v_sub_f32_e32 v98, v163, v98
	v_cmp_gt_i32_e32 vcc, v97, v166
	v_sub_f32_e32 v97, v163, v99
	v_fmac_f32_e32 v98, 0x3e38aa3b, v80
	s_and_b64 vcc, s[50:51], vcc
	v_fmac_f32_e32 v97, 0x3e38aa3b, v81
	v_add_u32_e32 v81, 0xffffffa1, v200
	v_cndmask_b32_e32 v80, v98, v192, vcc
	v_cmp_gt_i32_e32 vcc, v81, v166
	s_and_b64 vcc, s[50:51], vcc
	s_waitcnt lgkmcnt(0)
	v_sub_f32_e32 v98, v163, v102
	v_cndmask_b32_e32 v81, v97, v192, vcc
	v_sub_f32_e32 v97, v163, v100
	v_fmac_f32_e32 v97, 0x3e38aa3b, v82
	v_add_u32_e32 v82, 0xffffffa2, v200
	v_cmp_gt_i32_e32 vcc, v82, v166
	s_and_b64 vcc, s[50:51], vcc
	v_fmac_f32_e32 v98, 0x3e38aa3b, v84
	v_cndmask_b32_e32 v82, v97, v192, vcc
	v_sub_f32_e32 v97, v163, v101
	v_fmac_f32_e32 v97, 0x3e38aa3b, v83
	v_add_u32_e32 v83, 0xffffffa3, v200
	v_cmp_gt_i32_e32 vcc, v83, v166
	s_and_b64 vcc, s[50:51], vcc
	v_mfma_f32_32x32x16_bf16 v[64:79], v[206:209], v[116:119], v[64:79]
	v_cndmask_b32_e32 v83, v97, v192, vcc
	v_add_u32_e32 v97, 0xffffffa8, v200
	v_cmp_gt_i32_e32 vcc, v97, v166
	v_sub_f32_e32 v97, v163, v103
	s_and_b64 vcc, s[50:51], vcc
	v_fmac_f32_e32 v97, 0x3e38aa3b, v85
	v_add_u32_e32 v85, 0xffffffa9, v200
	v_cndmask_b32_e32 v84, v98, v192, vcc
	v_cmp_gt_i32_e32 vcc, v85, v166
	s_and_b64 vcc, s[50:51], vcc
	ds_read_b128 v[98:101], v199 offset:43200
	v_cndmask_b32_e32 v85, v97, v192, vcc
	v_sub_f32_e32 v97, v163, v104
	v_fmac_f32_e32 v97, 0x3e38aa3b, v86
	v_add_u32_e32 v86, 0xffffffaa, v200
	v_cmp_gt_i32_e32 vcc, v86, v166
	s_and_b64 vcc, s[50:51], vcc
	v_mfma_f32_32x32x16_bf16 v[64:79], v[222:225], v[120:123], v[64:79]
	v_cndmask_b32_e32 v86, v97, v192, vcc
	v_sub_f32_e32 v97, v163, v105
	v_fmac_f32_e32 v97, 0x3e38aa3b, v87
	v_add_u32_e32 v87, 0xffffffab, v200
	v_cmp_gt_i32_e32 vcc, v87, v166
	s_and_b64 vcc, s[50:51], vcc
	ds_read_b128 v[102:105], v199 offset:43232
	v_cndmask_b32_e32 v87, v97, v192, vcc
	v_add_u32_e32 v97, 0xffffffb0, v200
	s_waitcnt lgkmcnt(1)
	v_sub_f32_e32 v98, v163, v98
	v_fmac_f32_e32 v98, 0x3e38aa3b, v88
	v_cmp_gt_i32_e32 vcc, v97, v166
	v_sub_f32_e32 v88, v163, v99
	s_and_b64 vcc, s[50:51], vcc
	v_fmac_f32_e32 v88, 0x3e38aa3b, v89
	v_add_u32_e32 v89, 0xffffffb1, v200
	v_cndmask_b32_e32 v97, v98, v192, vcc
	v_cmp_gt_i32_e32 vcc, v89, v166
	s_and_b64 vcc, s[50:51], vcc
	v_add_u32_e32 v89, 0xffffffb2, v200
	v_cndmask_b32_e32 v98, v88, v192, vcc
	v_sub_f32_e32 v88, v163, v100
	v_cmp_gt_i32_e32 vcc, v89, v166
	v_fmac_f32_e32 v88, 0x3e38aa3b, v90
	s_and_b64 vcc, s[50:51], vcc
	v_add_u32_e32 v89, 0xffffffb3, v200
	v_cndmask_b32_e32 v99, v88, v192, vcc
	v_sub_f32_e32 v88, v163, v101
	v_cmp_gt_i32_e32 vcc, v89, v166
	v_fmac_f32_e32 v88, 0x3e38aa3b, v91
	s_and_b64 vcc, s[50:51], vcc
	v_cndmask_b32_e32 v100, v88, v192, vcc
	v_add_u32_e32 v88, 0xffffffb8, v200
	s_waitcnt lgkmcnt(0)
	v_sub_f32_e32 v89, v163, v102
	v_cmp_gt_i32_e32 vcc, v88, v166
	v_fmac_f32_e32 v89, 0x3e38aa3b, v92
	s_and_b64 vcc, s[50:51], vcc
	v_cndmask_b32_e32 v101, v89, v192, vcc
	v_add_u32_e32 v89, 0xffffffb9, v200
	v_sub_f32_e32 v88, v163, v103
	v_cmp_gt_i32_e32 vcc, v89, v166
	v_fmac_f32_e32 v88, 0x3e38aa3b, v93
	s_and_b64 vcc, s[50:51], vcc
	v_add_u32_e32 v89, 0xffffffba, v200
	v_mfma_f32_32x32x16_bf16 v[64:79], v[226:229], v[124:127], v[64:79]
	v_cndmask_b32_e32 v102, v88, v192, vcc
	v_sub_f32_e32 v88, v163, v104
	v_cmp_gt_i32_e32 vcc, v89, v166
	v_fmac_f32_e32 v88, 0x3e38aa3b, v94
	s_and_b64 vcc, s[50:51], vcc
	v_cndmask_b32_e32 v103, v88, v192, vcc
	v_sub_f32_e32 v88, v163, v105
	ds_read_b128 v[104:107], v199 offset:43264
	ds_read_b128 v[108:111], v199 offset:43296
	v_add_u32_e32 v89, 0xffffffbb, v200
	v_cmp_gt_i32_e32 vcc, v89, v166
	v_fmac_f32_e32 v88, 0x3e38aa3b, v95
	s_and_b64 vcc, s[50:51], vcc
	v_subrev_u32_e32 v89, 64, v200
	s_waitcnt lgkmcnt(1)
	v_sub_f32_e32 v90, v163, v104
	v_cndmask_b32_e32 v88, v88, v192, vcc
	v_fmac_f32_e32 v90, 0x3e38aa3b, v64
	v_cmp_gt_i32_e32 vcc, v89, v166
	v_sub_f32_e32 v64, v163, v105
	s_and_b64 vcc, s[50:51], vcc
	v_fmac_f32_e32 v64, 0x3e38aa3b, v65
	v_subrev_u32_e32 v65, 63, v200
	v_cndmask_b32_e32 v94, v90, v192, vcc
	v_cmp_gt_i32_e32 vcc, v65, v166
	s_and_b64 vcc, s[50:51], vcc
	v_subrev_u32_e32 v65, 62, v200
	v_cndmask_b32_e32 v92, v64, v192, vcc
	v_sub_f32_e32 v64, v163, v106
	v_cmp_gt_i32_e32 vcc, v65, v166
	v_fmac_f32_e32 v64, 0x3e38aa3b, v66
	s_and_b64 vcc, s[50:51], vcc
	v_subrev_u32_e32 v65, 61, v200
	v_cndmask_b32_e32 v93, v64, v192, vcc
	v_sub_f32_e32 v64, v163, v107
	v_cmp_gt_i32_e32 vcc, v65, v166
	v_fmac_f32_e32 v64, 0x3e38aa3b, v67
	s_and_b64 vcc, s[50:51], vcc
	v_cndmask_b32_e32 v91, v64, v192, vcc
	v_subrev_u32_e32 v64, 56, v200
	s_waitcnt lgkmcnt(0)
	v_sub_f32_e32 v65, v163, v108
	v_cmp_gt_i32_e32 vcc, v64, v166
	v_fmac_f32_e32 v65, 0x3e38aa3b, v68
	s_and_b64 vcc, s[50:51], vcc
	v_cndmask_b32_e32 v89, v65, v192, vcc
	v_subrev_u32_e32 v65, 55, v200
	v_sub_f32_e32 v64, v163, v109
	v_cmp_gt_i32_e32 vcc, v65, v166
	v_mfma_f32_32x32x16_bf16 v[48:63], v[52:55], v[112:115], 0
	v_fmac_f32_e32 v64, 0x3e38aa3b, v69
	s_and_b64 vcc, s[50:51], vcc
	v_subrev_u32_e32 v65, 54, v200
	v_cndmask_b32_e32 v90, v64, v192, vcc
	v_sub_f32_e32 v64, v163, v110
	v_cmp_gt_i32_e32 vcc, v65, v166
	v_fmac_f32_e32 v64, 0x3e38aa3b, v70
	s_and_b64 vcc, s[50:51], vcc
	v_cndmask_b32_e32 v67, v64, v192, vcc
	v_sub_f32_e32 v64, v163, v111
	v_fmac_f32_e32 v64, 0x3e38aa3b, v71
	ds_read_b128 v[68:71], v199 offset:43328
	ds_read_b128 v[104:107], v199 offset:43360
	v_subrev_u32_e32 v65, 53, v200
	v_cmp_gt_i32_e32 vcc, v65, v166
	v_mfma_f32_32x32x16_bf16 v[48:63], v[210:213], v[116:119], v[48:63]
	s_and_b64 vcc, s[50:51], vcc
	v_subrev_u32_e32 v65, 48, v200
	v_cndmask_b32_e32 v64, v64, v192, vcc
	s_waitcnt lgkmcnt(1)
	v_sub_f32_e32 v66, v163, v68
	v_cmp_gt_i32_e32 vcc, v65, v166
	v_fmac_f32_e32 v66, 0x3e38aa3b, v72
	s_and_b64 vcc, s[50:51], vcc
	v_cndmask_b32_e32 v72, v66, v192, vcc
	v_subrev_u32_e32 v66, 47, v200
	v_sub_f32_e32 v65, v163, v69
	v_cmp_gt_i32_e32 vcc, v66, v166
	v_fmac_f32_e32 v65, 0x3e38aa3b, v73
	s_and_b64 vcc, s[50:51], vcc
	v_subrev_u32_e32 v68, 46, v200
	v_cndmask_b32_e32 v66, v65, v192, vcc
	v_sub_f32_e32 v65, v163, v70
	v_cmp_gt_i32_e32 vcc, v68, v166
	v_fmac_f32_e32 v65, 0x3e38aa3b, v74
	s_and_b64 vcc, s[50:51], vcc
	v_subrev_u32_e32 v69, 45, v200
	v_mfma_f32_32x32x16_bf16 v[48:63], v[230:233], v[120:123], v[48:63]
	v_cndmask_b32_e32 v68, v65, v192, vcc
	v_sub_f32_e32 v65, v163, v71
	v_cmp_gt_i32_e32 vcc, v69, v166
	v_fmac_f32_e32 v65, 0x3e38aa3b, v75
	s_and_b64 vcc, s[50:51], vcc
	v_cndmask_b32_e32 v71, v65, v192, vcc
	v_subrev_u32_e32 v65, 40, v200
	s_waitcnt lgkmcnt(0)
	v_sub_f32_e32 v69, v163, v104
	v_cmp_gt_i32_e32 vcc, v65, v166
	v_fmac_f32_e32 v69, 0x3e38aa3b, v76
	s_and_b64 vcc, s[50:51], vcc
	v_cndmask_b32_e32 v73, v69, v192, vcc
	v_subrev_u32_e32 v69, 39, v200
	v_sub_f32_e32 v65, v163, v105
	v_cmp_gt_i32_e32 vcc, v69, v166
	v_fmac_f32_e32 v65, 0x3e38aa3b, v77
	s_and_b64 vcc, s[50:51], vcc
	v_subrev_u32_e32 v69, 38, v200
	v_mfma_f32_32x32x16_bf16 v[48:63], v[238:241], v[124:127], v[48:63]
	v_cndmask_b32_e32 v70, v65, v192, vcc
	v_sub_f32_e32 v65, v163, v106
	v_cmp_gt_i32_e32 vcc, v69, v166
	v_fmac_f32_e32 v65, 0x3e38aa3b, v78
	s_and_b64 vcc, s[50:51], vcc
	v_subrev_u32_e32 v74, 37, v200
	v_cndmask_b32_e32 v65, v65, v192, vcc
	v_cmp_gt_i32_e32 vcc, v74, v166
	ds_read_b128 v[74:77], v199 offset:43392
	v_sub_f32_e32 v69, v163, v107
	v_fmac_f32_e32 v69, 0x3e38aa3b, v79
	s_and_b64 vcc, s[50:51], vcc
	v_subrev_u32_e32 v78, 32, v200
	ds_read_b128 v[104:107], v199 offset:43424
	s_waitcnt lgkmcnt(1)
	v_sub_f32_e32 v74, v163, v74
	v_cndmask_b32_e32 v69, v69, v192, vcc
	v_fmac_f32_e32 v74, 0x3e38aa3b, v48
	v_cmp_gt_i32_e32 vcc, v78, v166
	v_sub_f32_e32 v48, v163, v75
	s_and_b64 vcc, s[50:51], vcc
	v_fmac_f32_e32 v48, 0x3e38aa3b, v49
	v_subrev_u32_e32 v49, 31, v200
	v_cndmask_b32_e32 v74, v74, v192, vcc
	v_cmp_gt_i32_e32 vcc, v49, v166
	s_and_b64 vcc, s[50:51], vcc
	v_subrev_u32_e32 v49, 30, v200
	v_cndmask_b32_e32 v75, v48, v192, vcc
	v_sub_f32_e32 v48, v163, v76
	v_cmp_gt_i32_e32 vcc, v49, v166
	v_fmac_f32_e32 v48, 0x3e38aa3b, v50
	s_and_b64 vcc, s[50:51], vcc
	v_subrev_u32_e32 v49, 29, v200
	v_cndmask_b32_e32 v76, v48, v192, vcc
	v_sub_f32_e32 v48, v163, v77
	v_cmp_gt_i32_e32 vcc, v49, v166
	v_fmac_f32_e32 v48, 0x3e38aa3b, v51
	s_and_b64 vcc, s[50:51], vcc
	v_cndmask_b32_e32 v50, v48, v192, vcc
	v_subrev_u32_e32 v48, 24, v200
	s_waitcnt lgkmcnt(0)
	v_sub_f32_e32 v49, v163, v104
	v_cmp_gt_i32_e32 vcc, v48, v166
	v_fmac_f32_e32 v49, 0x3e38aa3b, v52
	s_and_b64 vcc, s[50:51], vcc
	v_subrev_u32_e32 v51, 23, v200
	v_cndmask_b32_e32 v48, v49, v192, vcc
	v_sub_f32_e32 v49, v163, v105
	v_cmp_gt_i32_e32 vcc, v51, v166
	v_fmac_f32_e32 v49, 0x3e38aa3b, v53
	s_and_b64 vcc, s[50:51], vcc
	v_subrev_u32_e32 v52, 22, v200
	v_cndmask_b32_e32 v49, v49, v192, vcc
	v_sub_f32_e32 v51, v163, v106
	v_cmp_gt_i32_e32 vcc, v52, v166
	v_sub_f32_e32 v52, v163, v107
	ds_read_b128 v[104:107], v199 offset:43456
	ds_read_b128 v[108:111], v199 offset:43488
	v_fmac_f32_e32 v51, 0x3e38aa3b, v54
	s_and_b64 vcc, s[50:51], vcc
	v_subrev_u32_e32 v53, 21, v200
	v_cndmask_b32_e32 v51, v51, v192, vcc
	v_cmp_gt_i32_e32 vcc, v53, v166
	v_fmac_f32_e32 v52, 0x3e38aa3b, v55
	s_and_b64 vcc, s[50:51], vcc
	v_add_u32_e32 v53, -16, v200
	v_cndmask_b32_e32 v52, v52, v192, vcc
	s_waitcnt lgkmcnt(1)
	v_sub_f32_e32 v54, v163, v104
	v_cmp_gt_i32_e32 vcc, v53, v166
	v_fmac_f32_e32 v54, 0x3e38aa3b, v56
	s_and_b64 vcc, s[50:51], vcc
	v_cndmask_b32_e32 v77, v54, v192, vcc
	v_add_u32_e32 v54, -15, v200
	v_sub_f32_e32 v53, v163, v105
	v_cmp_gt_i32_e32 vcc, v54, v166
	v_fmac_f32_e32 v53, 0x3e38aa3b, v57
	s_and_b64 vcc, s[50:51], vcc
	v_add_u32_e32 v54, -14, v200
	v_cndmask_b32_e32 v56, v53, v192, vcc
	v_sub_f32_e32 v53, v163, v106
	v_cmp_gt_i32_e32 vcc, v54, v166
	v_fmac_f32_e32 v53, 0x3e38aa3b, v58
	s_and_b64 vcc, s[50:51], vcc
	v_add_u32_e32 v55, -13, v200
	v_cndmask_b32_e32 v53, v53, v192, vcc
	v_sub_f32_e32 v54, v163, v107
	v_cmp_gt_i32_e32 vcc, v55, v166
	v_fmac_f32_e32 v54, 0x3e38aa3b, v59
	s_and_b64 vcc, s[50:51], vcc
	v_add_u32_e32 v55, -8, v200
	v_cndmask_b32_e32 v54, v54, v192, vcc
	s_waitcnt lgkmcnt(0)
	v_sub_f32_e32 v57, v163, v108
	v_cmp_gt_i32_e32 vcc, v55, v166
	v_fmac_f32_e32 v57, 0x3e38aa3b, v60
	s_and_b64 vcc, s[50:51], vcc
	v_add_u32_e32 v58, -7, v200
	v_cndmask_b32_e32 v55, v57, v192, vcc
	v_sub_f32_e32 v57, v163, v109
	v_cmp_gt_i32_e32 vcc, v58, v166
	v_fmac_f32_e32 v57, 0x3e38aa3b, v61
	s_and_b64 vcc, s[50:51], vcc
	v_add_u32_e32 v59, -6, v200
	v_cndmask_b32_e32 v58, v57, v192, vcc
	v_sub_f32_e32 v57, v163, v110
	v_cmp_gt_i32_e32 vcc, v59, v166
	v_fmac_f32_e32 v57, 0x3e38aa3b, v62
	s_and_b64 vcc, s[50:51], vcc
	v_add_u32_e32 v60, -5, v200
	v_max_f32_e32 v62, v92, v75
	v_cndmask_b32_e32 v59, v57, v192, vcc
	v_cmp_gt_i32_e32 vcc, v60, v166
	v_max_f32_e32 v60, v1, v80
	v_max_f32_e32 v61, v94, v74
	v_max3_f32 v62, v2, v81, v62
	v_max3_f32 v60, v60, v61, v62
	v_max_f32_e32 v61, v93, v76
	v_max_f32_e32 v62, v91, v50
	v_max3_f32 v61, v3, v82, v61
	v_max3_f32 v62, v4, v83, v62
	v_max3_f32 v60, v60, v61, v62
	v_max_f32_e32 v61, v89, v48
	v_max_f32_e32 v62, v90, v49
	v_max3_f32 v61, v5, v84, v61
	v_max3_f32 v62, v6, v85, v62
	v_max3_f32 v60, v60, v61, v62
	v_max_f32_e32 v61, v67, v51
	v_max_f32_e32 v62, v64, v52
	v_max3_f32 v61, v7, v86, v61
	v_max3_f32 v62, v8, v87, v62
	v_max3_f32 v60, v60, v61, v62
	v_max_f32_e32 v61, v72, v77
	v_max_f32_e32 v62, v66, v56
	v_max3_f32 v61, v9, v97, v61
	v_max3_f32 v62, v10, v98, v62
	v_max3_f32 v60, v60, v61, v62
	v_max_f32_e32 v61, v68, v53
	v_max_f32_e32 v62, v71, v54
	v_sub_f32_e32 v57, v163, v111
	v_max3_f32 v61, v11, v99, v61
	v_max3_f32 v62, v12, v100, v62
	v_fmac_f32_e32 v57, 0x3e38aa3b, v63
	s_and_b64 vcc, s[50:51], vcc
	v_max3_f32 v60, v60, v61, v62
	v_max_f32_e32 v61, v73, v55
	v_max_f32_e32 v62, v70, v58
	v_cndmask_b32_e32 v57, v57, v192, vcc
	v_max3_f32 v61, v13, v101, v61
	v_max3_f32 v62, v14, v102, v62
	v_max3_f32 v60, v60, v61, v62
	v_max_f32_e32 v61, v65, v59
	v_max_f32_e32 v62, v69, v57
	v_max3_f32 v61, v15, v103, v61
	v_max3_f32 v62, v96, v88, v62
	v_max3_f32 v60, v60, v61, v62
	v_mov_b32_e32 v61, v60
	s_nop 1
	v_permlane32_swap_b32 v61, v60
	s_nop 1
	s_nop 0
	v_max_f32_e32 v60, v60, v60
	v_max_f32_e32 v61, v61, v61
	v_max_f32_e32 v60, v61, v60
	v_cmp_lt_f32_e32 vcc, s62, v60
	s_or_b64 s[20:21], s[24:25], vcc
	v_cndmask_b32_e64 v61, 0, 1, s[20:21]
	v_cmp_ne_u32_e32 vcc, 0, v61
.Lfox_join_F0:
	s_cbranch_vccz .LBB0_962
	s_mov_b32 s20, 0x41000000
	v_cmp_lt_f32_e32 vcc, s20, v60
	s_or_b64 vcc, s[24:25], vcc
	s_nop 0
	v_cndmask_b32_e32 v60, 0, v60, vcc
	v_cmp_neq_f32_e32 vcc, 0, v60
	s_cbranch_vccz .LBB0_961
	v_exp_f32_e64 v61, -v60
	v_sub_f32_e32 v1, v1, v60
	v_sub_f32_e32 v2, v2, v60
	v_sub_f32_e32 v3, v3, v60
	v_cndmask_b32_e64 v62, v61, 0, s[24:25]
	v_pk_mul_f32 v[30:31], v[30:31], v[62:63] op_sel_hi:[1,0]
	v_pk_mul_f32 v[28:29], v[28:29], v[62:63] op_sel_hi:[1,0]
	v_pk_mul_f32 v[26:27], v[26:27], v[62:63] op_sel_hi:[1,0]
	v_pk_mul_f32 v[24:25], v[24:25], v[62:63] op_sel_hi:[1,0]
	v_pk_mul_f32 v[22:23], v[22:23], v[62:63] op_sel_hi:[1,0]
	v_pk_mul_f32 v[20:21], v[20:21], v[62:63] op_sel_hi:[1,0]
	v_pk_mul_f32 v[18:19], v[18:19], v[62:63] op_sel_hi:[1,0]
	v_pk_mul_f32 v[16:17], v[16:17], v[62:63] op_sel_hi:[1,0]
	v_sub_f32_e32 v4, v4, v60
	v_sub_f32_e32 v5, v5, v60
	v_sub_f32_e32 v6, v6, v60
	v_sub_f32_e32 v7, v7, v60
	v_sub_f32_e32 v8, v8, v60
	v_sub_f32_e32 v9, v9, v60
	v_sub_f32_e32 v10, v10, v60
	v_sub_f32_e32 v11, v11, v60
	v_sub_f32_e32 v12, v12, v60
	v_sub_f32_e32 v13, v13, v60
	v_sub_f32_e32 v14, v14, v60
	v_sub_f32_e32 v15, v15, v60
	v_sub_f32_e32 v96, v96, v60
	v_sub_f32_e32 v80, v80, v60
	v_sub_f32_e32 v81, v81, v60
	v_sub_f32_e32 v82, v82, v60
	v_sub_f32_e32 v83, v83, v60
	v_sub_f32_e32 v84, v84, v60
	v_sub_f32_e32 v85, v85, v60
	v_sub_f32_e32 v86, v86, v60
	v_sub_f32_e32 v87, v87, v60
	v_sub_f32_e32 v97, v97, v60
	v_sub_f32_e32 v98, v98, v60
	v_sub_f32_e32 v99, v99, v60
	v_sub_f32_e32 v100, v100, v60
	v_sub_f32_e32 v101, v101, v60
	v_sub_f32_e32 v102, v102, v60
	v_sub_f32_e32 v103, v103, v60
	v_sub_f32_e32 v88, v88, v60
	v_sub_f32_e32 v94, v94, v60
	v_sub_f32_e32 v92, v92, v60
	v_sub_f32_e32 v93, v93, v60
	v_sub_f32_e32 v91, v91, v60
	v_sub_f32_e32 v89, v89, v60
	v_sub_f32_e32 v90, v90, v60
	v_sub_f32_e32 v67, v67, v60
	v_sub_f32_e32 v64, v64, v60
	v_sub_f32_e32 v72, v72, v60
	v_sub_f32_e32 v66, v66, v60
	v_sub_f32_e32 v68, v68, v60
	v_sub_f32_e32 v71, v71, v60
	v_sub_f32_e32 v73, v73, v60
	v_sub_f32_e32 v70, v70, v60
	v_sub_f32_e32 v65, v65, v60
	v_sub_f32_e32 v69, v69, v60
	v_sub_f32_e32 v74, v74, v60
	v_sub_f32_e32 v75, v75, v60
	v_sub_f32_e32 v76, v76, v60
	v_sub_f32_e32 v50, v50, v60
	v_sub_f32_e32 v48, v48, v60
	v_sub_f32_e32 v49, v49, v60
	v_sub_f32_e32 v51, v51, v60
	v_sub_f32_e32 v52, v52, v60
	v_sub_f32_e32 v77, v77, v60
	v_sub_f32_e32 v56, v56, v60
	v_sub_f32_e32 v53, v53, v60
	v_sub_f32_e32 v54, v54, v60
	v_sub_f32_e32 v55, v55, v60
	v_sub_f32_e32 v58, v58, v60
	v_sub_f32_e32 v59, v59, v60
	v_sub_f32_e32 v57, v57, v60
	v_pk_mul_f32 v[46:47], v[46:47], v[62:63] op_sel_hi:[1,0]
	v_pk_mul_f32 v[44:45], v[44:45], v[62:63] op_sel_hi:[1,0]
	v_pk_mul_f32 v[42:43], v[42:43], v[62:63] op_sel_hi:[1,0]
	v_pk_mul_f32 v[40:41], v[40:41], v[62:63] op_sel_hi:[1,0]
	v_pk_mul_f32 v[38:39], v[38:39], v[62:63] op_sel_hi:[1,0]
	v_pk_mul_f32 v[36:37], v[36:37], v[62:63] op_sel_hi:[1,0]
	v_pk_mul_f32 v[34:35], v[34:35], v[62:63] op_sel_hi:[1,0]
	v_pk_mul_f32 v[32:33], v[32:33], v[62:63] op_sel_hi:[1,0]
	v_mul_f32_e32 v195, v195, v62
	v_sub_f32_e32 v163, v163, v60

.LBB0_3058:
	s_and_b32 s37, s37, 1
	s_cmp_gt_i32 s9, s6
	s_cselect_b64 s[38:39], -1, 0
	s_or_b64 s[38:39], s[38:39], s[30:31]
	s_and_b64 vcc, exec, s[38:39]
	s_cbranch_vccnz .LBB0_3064
	s_add_i32 s30, s8, s7
	s_cmp_gt_i32 s30, s1
	s_cbranch_scc1 .Lfox_mask_F1
	s_mul_i32 s30, s37, 0xaa00
	s_add_i32 s38, s30, 0
	v_add_u32_e32 v13, s38, v179
	v_add_u32_e32 v1, v13, v180
	ds_read_b128 v[2:5], v1
	ds_read_b128 v[6:9], v1 offset:32
	s_add_i32 s30, s8, s7
	v_add_u32_e32 v199, s8, v196
	s_cmp_gt_i32 s30, s1
	s_waitcnt lgkmcnt(1)
	v_mfma_f32_32x32x16_bf16 v[96:111], v[2:5], v[112:115], 0
	ds_read_b128 v[2:5], v1 offset:4608
	s_cselect_b64 s[30:31], -1, 0
	s_waitcnt lgkmcnt(1)
	v_mfma_f32_32x32x16_bf16 v[96:111], v[6:9], v[116:119], v[96:111]
	s_waitcnt lgkmcnt(0)
	v_mfma_f32_32x32x16_bf16 v[80:95], v[2:5], v[112:115], 0
	ds_read_b128 v[2:5], v1 offset:9216
	s_waitcnt lgkmcnt(0)
	v_mfma_f32_32x32x16_bf16 v[64:79], v[2:5], v[112:115], 0
	ds_read_b128 v[2:5], v1 offset:13824
	s_waitcnt lgkmcnt(0)
	v_mfma_f32_32x32x16_bf16 v[48:63], v[2:5], v[112:115], 0
	ds_read_b128 v[2:5], v1 offset:4640
	s_waitcnt lgkmcnt(0)
	v_mfma_f32_32x32x16_bf16 v[80:95], v[2:5], v[116:119], v[80:95]
	ds_read_b128 v[2:5], v1 offset:9248
	s_waitcnt lgkmcnt(0)
	v_mfma_f32_32x32x16_bf16 v[64:79], v[2:5], v[116:119], v[64:79]
	ds_read_b128 v[2:5], v1 offset:13856
	s_waitcnt lgkmcnt(0)
	v_mfma_f32_32x32x16_bf16 v[48:63], v[2:5], v[116:119], v[48:63]
	ds_read_b128 v[2:5], v1 offset:64
	s_waitcnt lgkmcnt(0)
	v_mfma_f32_32x32x16_bf16 v[96:111], v[2:5], v[120:123], v[96:111]
	ds_read_b128 v[2:5], v1 offset:4672
	s_waitcnt lgkmcnt(0)
	v_mfma_f32_32x32x16_bf16 v[80:95], v[2:5], v[120:123], v[80:95]
	ds_read_b128 v[2:5], v1 offset:9280
	s_waitcnt lgkmcnt(0)
	v_mfma_f32_32x32x16_bf16 v[64:79], v[2:5], v[120:123], v[64:79]
	ds_read_b128 v[2:5], v1 offset:13888
	s_waitcnt lgkmcnt(0)
	v_mfma_f32_32x32x16_bf16 v[48:63], v[2:5], v[120:123], v[48:63]
	ds_read_b128 v[2:5], v1 offset:96
	s_waitcnt lgkmcnt(0)
	v_mfma_f32_32x32x16_bf16 v[96:111], v[2:5], v[124:127], v[96:111]
	ds_read_b128 v[2:5], v1 offset:4704
	s_waitcnt lgkmcnt(0)
	v_mfma_f32_32x32x16_bf16 v[80:95], v[2:5], v[124:127], v[80:95]
	ds_read_b128 v[2:5], v1 offset:9312
	s_waitcnt lgkmcnt(0)
	v_mfma_f32_32x32x16_bf16 v[64:79], v[2:5], v[124:127], v[64:79]
	ds_read_b128 v[2:5], v1 offset:13920
	s_waitcnt lgkmcnt(0)
	v_mfma_f32_32x32x16_bf16 v[48:63], v[2:5], v[124:127], v[48:63]
	ds_read_b128 v[2:5], v13 offset:43008
	ds_read_b128 v[6:9], v13 offset:43040
	s_waitcnt lgkmcnt(1)
	v_sub_f32_e32 v1, v163, v2
	v_fmac_f32_e32 v1, 0x3e38aa3b, v96
	v_sub_f32_e32 v2, v163, v3
	v_fmac_f32_e32 v2, 0x3e38aa3b, v97
	v_sub_f32_e32 v3, v163, v4
	v_fmac_f32_e32 v3, 0x3e38aa3b, v98
	v_sub_f32_e32 v4, v163, v5
	v_fmac_f32_e32 v4, 0x3e38aa3b, v99
	s_waitcnt lgkmcnt(0)
	v_sub_f32_e32 v6, v163, v6
	v_fmac_f32_e32 v6, 0x3e38aa3b, v100
	v_mov_b32_e32 v5, v6
	v_sub_f32_e32 v6, v163, v7
	v_fmac_f32_e32 v6, 0x3e38aa3b, v101
	v_sub_f32_e32 v7, v163, v8
	ds_read_b128 v[96:99], v13 offset:43072
	v_fmac_f32_e32 v7, 0x3e38aa3b, v102
	v_sub_f32_e32 v8, v163, v9
	v_fmac_f32_e32 v8, 0x3e38aa3b, v103
	s_waitcnt lgkmcnt(0)
	v_sub_f32_e32 v10, v163, v96
	v_fmac_f32_e32 v10, 0x3e38aa3b, v104
	v_mov_b32_e32 v9, v10
	v_sub_f32_e32 v10, v163, v97
	v_fmac_f32_e32 v10, 0x3e38aa3b, v105
	v_sub_f32_e32 v11, v163, v98
	v_sub_f32_e32 v12, v163, v99
	ds_read_b128 v[96:99], v13 offset:43104
	v_fmac_f32_e32 v11, 0x3e38aa3b, v106
	v_fmac_f32_e32 v12, 0x3e38aa3b, v107
	s_waitcnt lgkmcnt(0)
	v_sub_f32_e32 v15, v163, v96
	v_fmac_f32_e32 v15, 0x3e38aa3b, v108
	v_mov_b32_e32 v14, v15
	v_sub_f32_e32 v15, v163, v97
	v_fmac_f32_e32 v15, 0x3e38aa3b, v109
	v_sub_f32_e32 v96, v163, v98
	v_fmac_f32_e32 v96, 0x3e38aa3b, v110
	v_sub_f32_e32 v97, v163, v99
	ds_read_b128 v[98:101], v13 offset:43136
	v_fmac_f32_e32 v97, 0x3e38aa3b, v111
	s_waitcnt lgkmcnt(0)
	v_sub_f32_e32 v98, v163, v98
	v_fmac_f32_e32 v98, 0x3e38aa3b, v80
	v_mov_b32_e32 v80, v98
	v_sub_f32_e32 v98, v163, v99
	v_fmac_f32_e32 v98, 0x3e38aa3b, v81
	v_mov_b32_e32 v81, v98
	v_sub_f32_e32 v98, v163, v100
	v_fmac_f32_e32 v98, 0x3e38aa3b, v82
	s_nop 0
	v_mov_b32_e32 v82, v98
	v_sub_f32_e32 v98, v163, v101
	v_fmac_f32_e32 v98, 0x3e38aa3b, v83
	s_nop 0
	v_mov_b32_e32 v83, v98
	ds_read_b128 v[98:101], v13 offset:43168
	s_waitcnt lgkmcnt(0)
	v_sub_f32_e32 v98, v163, v98
	v_fmac_f32_e32 v98, 0x3e38aa3b, v84
	v_mov_b32_e32 v84, v98
	v_sub_f32_e32 v98, v163, v99
	v_fmac_f32_e32 v98, 0x3e38aa3b, v85
	s_nop 0
	v_mov_b32_e32 v85, v98
	v_sub_f32_e32 v98, v163, v100
	v_fmac_f32_e32 v98, 0x3e38aa3b, v86
	s_nop 0
	v_mov_b32_e32 v86, v98
	v_sub_f32_e32 v98, v163, v101
	v_fmac_f32_e32 v98, 0x3e38aa3b, v87
	s_nop 0
	v_mov_b32_e32 v87, v98
	ds_read_b128 v[98:101], v13 offset:43200
	s_waitcnt lgkmcnt(0)
	v_sub_f32_e32 v98, v163, v98
	v_fmac_f32_e32 v98, 0x3e38aa3b, v88
	v_mov_b32_e32 v88, v98
	v_sub_f32_e32 v98, v163, v99
	v_fmac_f32_e32 v98, 0x3e38aa3b, v89
	s_nop 0
	v_mov_b32_e32 v89, v98
	v_sub_f32_e32 v98, v163, v100
	v_fmac_f32_e32 v98, 0x3e38aa3b, v90
	s_nop 0
	v_mov_b32_e32 v90, v98
	v_sub_f32_e32 v98, v163, v101
	v_fmac_f32_e32 v98, 0x3e38aa3b, v91
	s_nop 0
	v_mov_b32_e32 v91, v98
	ds_read_b128 v[98:101], v13 offset:43232
	s_waitcnt lgkmcnt(0)
	v_sub_f32_e32 v98, v163, v98
	v_fmac_f32_e32 v98, 0x3e38aa3b, v92
	v_sub_f32_e32 v92, v163, v99
	v_fmac_f32_e32 v92, 0x3e38aa3b, v93
	v_mov_b32_e32 v99, v92
	v_sub_f32_e32 v92, v163, v100
	v_fmac_f32_e32 v92, 0x3e38aa3b, v94
	v_mov_b32_e32 v94, v92
	v_sub_f32_e32 v92, v163, v101
	ds_read_b128 v[100:103], v13 offset:43264
	v_fmac_f32_e32 v92, 0x3e38aa3b, v95
	s_waitcnt lgkmcnt(0)
	v_sub_f32_e32 v95, v163, v100
	v_fmac_f32_e32 v95, 0x3e38aa3b, v64
	v_sub_f32_e32 v64, v163, v101
	v_fmac_f32_e32 v64, 0x3e38aa3b, v65
	v_mov_b32_e32 v93, v95
	s_nop 0
	v_mov_b32_e32 v65, v64
	v_sub_f32_e32 v64, v163, v102
	v_fmac_f32_e32 v64, 0x3e38aa3b, v66
	s_nop 0
	v_mov_b32_e32 v66, v64
	v_sub_f32_e32 v64, v163, v103
	ds_read_b128 v[100:103], v13 offset:43296
	v_fmac_f32_e32 v64, 0x3e38aa3b, v67
	s_waitcnt lgkmcnt(0)
	v_sub_f32_e32 v95, v163, v100
	v_fmac_f32_e32 v95, 0x3e38aa3b, v68
	v_mov_b32_e32 v100, v95
	v_sub_f32_e32 v67, v163, v101
	v_fmac_f32_e32 v67, 0x3e38aa3b, v69
	v_mov_b32_e32 v101, v67
	v_sub_f32_e32 v67, v163, v102
	v_fmac_f32_e32 v67, 0x3e38aa3b, v70
	v_mov_b32_e32 v95, v67
	v_sub_f32_e32 v67, v163, v103
	ds_read_b128 v[102:105], v13 offset:43328
	v_fmac_f32_e32 v67, 0x3e38aa3b, v71
	v_mov_b32_e32 v69, v67
	s_waitcnt lgkmcnt(0)
	v_sub_f32_e32 v68, v163, v102
	v_fmac_f32_e32 v68, 0x3e38aa3b, v72
	v_mov_b32_e32 v71, v68
	v_sub_f32_e32 v67, v163, v103
	v_fmac_f32_e32 v67, 0x3e38aa3b, v73
	v_sub_f32_e32 v68, v163, v104
	v_sub_f32_e32 v70, v163, v105
	ds_read_b128 v[102:105], v13 offset:43360
	v_fmac_f32_e32 v68, 0x3e38aa3b, v74
	v_fmac_f32_e32 v70, 0x3e38aa3b, v75
	s_waitcnt lgkmcnt(0)
	v_sub_f32_e32 v73, v163, v102
	v_fmac_f32_e32 v73, 0x3e38aa3b, v76
	v_mov_b32_e32 v75, v73
	v_sub_f32_e32 v72, v163, v103
	v_fmac_f32_e32 v72, 0x3e38aa3b, v77
	v_mov_b32_e32 v74, v72
	v_sub_f32_e32 v72, v163, v104
	v_fmac_f32_e32 v72, 0x3e38aa3b, v78
	v_sub_f32_e32 v73, v163, v105
	v_fmac_f32_e32 v73, 0x3e38aa3b, v79
	ds_read_b128 v[76:79], v13 offset:43392
	ds_read_b128 v[102:105], v13 offset:43424
	s_waitcnt lgkmcnt(1)
	v_sub_f32_e32 v76, v163, v76
	v_fmac_f32_e32 v76, 0x3e38aa3b, v48
	v_mov_b32_e32 v48, v76
	v_sub_f32_e32 v76, v163, v77
	v_fmac_f32_e32 v76, 0x3e38aa3b, v49
	v_sub_f32_e32 v49, v163, v78
	v_fmac_f32_e32 v49, 0x3e38aa3b, v50
	s_waitcnt lgkmcnt(0)
	v_sub_f32_e32 v77, v163, v102
	v_mov_b32_e32 v50, v49
	v_sub_f32_e32 v49, v163, v79
	v_fmac_f32_e32 v49, 0x3e38aa3b, v51
	v_fmac_f32_e32 v77, 0x3e38aa3b, v52
	v_sub_f32_e32 v52, v163, v103
	v_fmac_f32_e32 v52, 0x3e38aa3b, v53
	v_mov_b32_e32 v51, v77
	v_sub_f32_e32 v53, v163, v104
	v_fmac_f32_e32 v53, 0x3e38aa3b, v54
	v_sub_f32_e32 v54, v163, v105
	ds_read_b128 v[102:105], v13 offset:43456
	v_fmac_f32_e32 v54, 0x3e38aa3b, v55
	s_waitcnt lgkmcnt(0)
	v_sub_f32_e32 v77, v163, v102
	v_fmac_f32_e32 v77, 0x3e38aa3b, v56
	v_sub_f32_e32 v55, v163, v103
	v_fmac_f32_e32 v55, 0x3e38aa3b, v57
	v_mov_b32_e32 v57, v55
	v_sub_f32_e32 v55, v163, v104
	v_sub_f32_e32 v56, v163, v105
	ds_read_b128 v[102:105], v13 offset:43488
	v_fmac_f32_e32 v55, 0x3e38aa3b, v58
	v_fmac_f32_e32 v56, 0x3e38aa3b, v59
	s_waitcnt lgkmcnt(0)
	v_sub_f32_e32 v58, v163, v102
	v_fmac_f32_e32 v58, 0x3e38aa3b, v60
	v_mov_b32_e32 v13, v58
	v_sub_f32_e32 v58, v163, v103
	v_fmac_f32_e32 v58, 0x3e38aa3b, v61
	v_mov_b32_e32 v59, v58
	v_sub_f32_e32 v58, v163, v104
	v_fmac_f32_e32 v58, 0x3e38aa3b, v62
	v_mov_b32_e32 v60, v58
	v_sub_f32_e32 v58, v163, v105
	v_fmac_f32_e32 v58, 0x3e38aa3b, v63
	v_max_f32_e32 v63, v65, v76
	v_max_f32_e32 v61, v1, v80
	v_max_f32_e32 v62, v93, v48
	v_max3_f32 v63, v2, v81, v63
	v_max3_f32 v61, v61, v62, v63
	v_max_f32_e32 v62, v66, v50
	v_max_f32_e32 v63, v64, v49
	v_max3_f32 v62, v3, v82, v62
	v_max3_f32 v63, v4, v83, v63
	v_max3_f32 v61, v61, v62, v63
	v_max_f32_e32 v62, v100, v51
	v_max_f32_e32 v63, v101, v52
	v_max3_f32 v62, v5, v84, v62
	v_max3_f32 v63, v6, v85, v63
	v_max3_f32 v61, v61, v62, v63
	v_max_f32_e32 v62, v95, v53
	v_max_f32_e32 v63, v69, v54
	v_max3_f32 v62, v7, v86, v62
	v_max3_f32 v63, v8, v87, v63
	v_max3_f32 v61, v61, v62, v63
	v_max_f32_e32 v62, v71, v77
	v_max_f32_e32 v63, v67, v57
	v_max3_f32 v62, v9, v88, v62
	v_max3_f32 v63, v10, v89, v63
	v_max3_f32 v61, v61, v62, v63
	v_max_f32_e32 v62, v68, v55
	v_max_f32_e32 v63, v70, v56
	v_max3_f32 v62, v11, v90, v62
	v_max3_f32 v63, v12, v91, v63
	v_max3_f32 v61, v61, v62, v63
	v_max_f32_e32 v62, v75, v13
	v_max_f32_e32 v63, v74, v59
	v_max3_f32 v62, v14, v98, v62
	v_max3_f32 v63, v15, v99, v63
	v_max3_f32 v61, v61, v62, v63
	v_max_f32_e32 v62, v72, v60
	v_max_f32_e32 v63, v73, v58
	v_max3_f32 v62, v96, v94, v62
	v_max3_f32 v63, v97, v92, v63
	v_max3_f32 v61, v61, v62, v63
	v_mov_b32_e32 v62, v61
	s_nop 1
	v_permlane32_swap_b32 v62, v61
	s_nop 1
	s_nop 0
	v_max_f32_e32 v61, v61, v61
	v_max_f32_e32 v62, v62, v62
	v_max_f32_e32 v61, v62, v61
	v_cmp_lt_f32_e32 vcc, s75, v61
	s_or_b64 s[30:31], s[28:29], vcc
	v_cndmask_b32_e64 v62, 0, 1, s[30:31]
	v_cmp_ne_u32_e32 vcc, 0, v62
	s_branch .Lfox_join_F1
.Lfox_mask_F1:
	s_mul_i32 s30, s37, 0xaa00
	s_add_i32 s38, s30, 0
	v_add_u32_e32 v13, s38, v179
	v_add_u32_e32 v1, v13, v180
	ds_read_b128 v[2:5], v1
	ds_read_b128 v[6:9], v1 offset:32
	s_add_i32 s30, s8, s7
	v_add_u32_e32 v199, s8, v196
	s_cmp_gt_i32 s30, s1
	s_waitcnt lgkmcnt(1)
	v_mfma_f32_32x32x16_bf16 v[96:111], v[2:5], v[112:115], 0
	ds_read_b128 v[2:5], v1 offset:4608
	v_add_u32_e32 v10, 0xffffff80, v199
	s_cselect_b64 s[30:31], -1, 0
	v_cmp_gt_i32_e32 vcc, v10, v166
	s_and_b64 vcc, s[30:31], vcc
	v_add_u32_e32 v11, 0xffffff91, v199
	v_add_u32_e32 v12, 0xffffff92, v199
	s_waitcnt lgkmcnt(1)
	v_mfma_f32_32x32x16_bf16 v[96:111], v[6:9], v[116:119], v[96:111]
	v_add_u32_e32 v14, 0xffffff93, v199
	s_waitcnt lgkmcnt(0)
	v_mfma_f32_32x32x16_bf16 v[80:95], v[2:5], v[112:115], 0
	ds_read_b128 v[2:5], v1 offset:9216
	s_waitcnt lgkmcnt(0)
	v_mfma_f32_32x32x16_bf16 v[64:79], v[2:5], v[112:115], 0
	ds_read_b128 v[2:5], v1 offset:13824
	s_waitcnt lgkmcnt(0)
	v_mfma_f32_32x32x16_bf16 v[48:63], v[2:5], v[112:115], 0
	ds_read_b128 v[2:5], v1 offset:4640
	s_waitcnt lgkmcnt(0)
	v_mfma_f32_32x32x16_bf16 v[80:95], v[2:5], v[116:119], v[80:95]
	ds_read_b128 v[2:5], v1 offset:9248
	s_waitcnt lgkmcnt(0)
	v_mfma_f32_32x32x16_bf16 v[64:79], v[2:5], v[116:119], v[64:79]
	ds_read_b128 v[2:5], v1 offset:13856
	s_waitcnt lgkmcnt(0)
	v_mfma_f32_32x32x16_bf16 v[48:63], v[2:5], v[116:119], v[48:63]
	ds_read_b128 v[2:5], v1 offset:64
	s_waitcnt lgkmcnt(0)
	v_mfma_f32_32x32x16_bf16 v[96:111], v[2:5], v[120:123], v[96:111]
	ds_read_b128 v[2:5], v1 offset:4672
	s_waitcnt lgkmcnt(0)
	v_mfma_f32_32x32x16_bf16 v[80:95], v[2:5], v[120:123], v[80:95]
	ds_read_b128 v[2:5], v1 offset:9280
	s_waitcnt lgkmcnt(0)
	v_mfma_f32_32x32x16_bf16 v[64:79], v[2:5], v[120:123], v[64:79]
	ds_read_b128 v[2:5], v1 offset:13888
	s_waitcnt lgkmcnt(0)
	v_mfma_f32_32x32x16_bf16 v[48:63], v[2:5], v[120:123], v[48:63]
	ds_read_b128 v[2:5], v1 offset:96
	s_waitcnt lgkmcnt(0)
	v_mfma_f32_32x32x16_bf16 v[96:111], v[2:5], v[124:127], v[96:111]
	ds_read_b128 v[2:5], v1 offset:4704
	s_waitcnt lgkmcnt(0)
	v_mfma_f32_32x32x16_bf16 v[80:95], v[2:5], v[124:127], v[80:95]
	ds_read_b128 v[2:5], v1 offset:9312
	s_waitcnt lgkmcnt(0)
	v_mfma_f32_32x32x16_bf16 v[64:79], v[2:5], v[124:127], v[64:79]
	ds_read_b128 v[2:5], v1 offset:13920
	s_waitcnt lgkmcnt(0)
	v_mfma_f32_32x32x16_bf16 v[48:63], v[2:5], v[124:127], v[48:63]
	ds_read_b128 v[2:5], v13 offset:43008
	ds_read_b128 v[6:9], v13 offset:43040
	s_waitcnt lgkmcnt(1)
	v_sub_f32_e32 v1, v163, v2
	v_fmac_f32_e32 v1, 0x3e38aa3b, v96
	v_cndmask_b32_e32 v1, v1, v192, vcc
	v_sub_f32_e32 v2, v163, v3
	v_cmp_ge_i32_e32 vcc, v10, v166
	v_fmac_f32_e32 v2, 0x3e38aa3b, v97
	s_and_b64 vcc, s[30:31], vcc
	v_sub_f32_e32 v3, v163, v4
	v_add_u32_e32 v4, 0xffffff82, v199
	v_cndmask_b32_e32 v2, v2, v192, vcc
	v_cmp_gt_i32_e32 vcc, v4, v166
	v_fmac_f32_e32 v3, 0x3e38aa3b, v98
	s_and_b64 vcc, s[30:31], vcc
	v_sub_f32_e32 v4, v163, v5
	v_add_u32_e32 v5, 0xffffff83, v199
	v_cndmask_b32_e32 v3, v3, v192, vcc
	v_cmp_gt_i32_e32 vcc, v5, v166
	v_fmac_f32_e32 v4, 0x3e38aa3b, v99
	s_and_b64 vcc, s[30:31], vcc
	v_add_u32_e32 v5, 0xffffff88, v199
	v_cndmask_b32_e32 v4, v4, v192, vcc
	s_waitcnt lgkmcnt(0)
	v_sub_f32_e32 v6, v163, v6
	v_cmp_gt_i32_e32 vcc, v5, v166
	v_fmac_f32_e32 v6, 0x3e38aa3b, v100
	s_and_b64 vcc, s[30:31], vcc
	v_cndmask_b32_e32 v5, v6, v192, vcc
	v_sub_f32_e32 v6, v163, v7
	v_add_u32_e32 v7, 0xffffff89, v199
	v_cmp_gt_i32_e32 vcc, v7, v166
	v_fmac_f32_e32 v6, 0x3e38aa3b, v101
	s_and_b64 vcc, s[30:31], vcc
	v_sub_f32_e32 v7, v163, v8
	v_add_u32_e32 v8, 0xffffff8a, v199
	ds_read_b128 v[96:99], v13 offset:43072
	v_cndmask_b32_e32 v6, v6, v192, vcc
	v_cmp_gt_i32_e32 vcc, v8, v166
	v_fmac_f32_e32 v7, 0x3e38aa3b, v102
	s_and_b64 vcc, s[30:31], vcc
	v_sub_f32_e32 v8, v163, v9
	v_add_u32_e32 v9, 0xffffff8b, v199
	v_cndmask_b32_e32 v7, v7, v192, vcc
	v_cmp_gt_i32_e32 vcc, v9, v166
	v_fmac_f32_e32 v8, 0x3e38aa3b, v103
	s_and_b64 vcc, s[30:31], vcc
	v_add_u32_e32 v9, 0xffffff90, v199
	v_cndmask_b32_e32 v8, v8, v192, vcc
	s_waitcnt lgkmcnt(0)
	v_sub_f32_e32 v10, v163, v96
	v_cmp_gt_i32_e32 vcc, v9, v166
	v_fmac_f32_e32 v10, 0x3e38aa3b, v104
	s_and_b64 vcc, s[30:31], vcc
	v_cndmask_b32_e32 v9, v10, v192, vcc
	v_sub_f32_e32 v10, v163, v97
	v_cmp_gt_i32_e32 vcc, v11, v166
	v_fmac_f32_e32 v10, 0x3e38aa3b, v105
	s_and_b64 vcc, s[30:31], vcc
	v_cndmask_b32_e32 v10, v10, v192, vcc
	v_sub_f32_e32 v11, v163, v98
	v_cmp_gt_i32_e32 vcc, v12, v166
	v_sub_f32_e32 v12, v163, v99
	ds_read_b128 v[96:99], v13 offset:43104
	v_fmac_f32_e32 v11, 0x3e38aa3b, v106
	s_and_b64 vcc, s[30:31], vcc
	v_cndmask_b32_e32 v11, v11, v192, vcc
	v_cmp_gt_i32_e32 vcc, v14, v166
	v_fmac_f32_e32 v12, 0x3e38aa3b, v107
	s_and_b64 vcc, s[30:31], vcc
	v_add_u32_e32 v14, 0xffffff98, v199
	v_cndmask_b32_e32 v12, v12, v192, vcc
	s_waitcnt lgkmcnt(0)
	v_sub_f32_e32 v15, v163, v96
	v_cmp_gt_i32_e32 vcc, v14, v166
	v_fmac_f32_e32 v15, 0x3e38aa3b, v108
	s_and_b64 vcc, s[30:31], vcc
	v_add_u32_e32 v96, 0xffffff99, v199
	v_cndmask_b32_e32 v14, v15, v192, vcc
	v_sub_f32_e32 v15, v163, v97
	v_cmp_gt_i32_e32 vcc, v96, v166
	v_fmac_f32_e32 v15, 0x3e38aa3b, v109
	s_and_b64 vcc, s[30:31], vcc
	v_add_u32_e32 v97, 0xffffff9a, v199
	v_cndmask_b32_e32 v15, v15, v192, vcc
	v_sub_f32_e32 v96, v163, v98
	v_cmp_gt_i32_e32 vcc, v97, v166
	v_fmac_f32_e32 v96, 0x3e38aa3b, v110
	s_and_b64 vcc, s[30:31], vcc
	v_add_u32_e32 v98, 0xffffff9b, v199
	v_cndmask_b32_e32 v96, v96, v192, vcc
	v_sub_f32_e32 v97, v163, v99
	v_cmp_gt_i32_e32 vcc, v98, v166
	ds_read_b128 v[98:101], v13 offset:43136
	v_fmac_f32_e32 v97, 0x3e38aa3b, v111
	s_and_b64 vcc, s[30:31], vcc
	v_add_u32_e32 v102, 0xffffffa0, v199
	v_cndmask_b32_e32 v97, v97, v192, vcc
	s_waitcnt lgkmcnt(0)
	v_sub_f32_e32 v98, v163, v98
	v_cmp_gt_i32_e32 vcc, v102, v166
	v_fmac_f32_e32 v98, 0x3e38aa3b, v80
	s_and_b64 vcc, s[30:31], vcc
	v_cndmask_b32_e32 v80, v98, v192, vcc
	v_sub_f32_e32 v98, v163, v99
	v_fmac_f32_e32 v98, 0x3e38aa3b, v81
	v_add_u32_e32 v81, 0xffffffa1, v199
	v_cmp_gt_i32_e32 vcc, v81, v166
	s_and_b64 vcc, s[30:31], vcc
	v_add_u32_e32 v102, 0xffffffa8, v199
	v_cndmask_b32_e32 v81, v98, v192, vcc
	v_sub_f32_e32 v98, v163, v100
	v_fmac_f32_e32 v98, 0x3e38aa3b, v82
	v_add_u32_e32 v82, 0xffffffa2, v199
	v_cmp_gt_i32_e32 vcc, v82, v166
	s_and_b64 vcc, s[30:31], vcc
	s_nop 0
	v_cndmask_b32_e32 v82, v98, v192, vcc
	v_sub_f32_e32 v98, v163, v101
	v_fmac_f32_e32 v98, 0x3e38aa3b, v83
	v_add_u32_e32 v83, 0xffffffa3, v199
	v_cmp_gt_i32_e32 vcc, v83, v166
	s_and_b64 vcc, s[30:31], vcc
	s_nop 0
	v_cndmask_b32_e32 v83, v98, v192, vcc
	ds_read_b128 v[98:101], v13 offset:43168
	v_cmp_gt_i32_e32 vcc, v102, v166
	s_and_b64 vcc, s[30:31], vcc
	v_add_u32_e32 v102, 0xffffffb0, v199
	s_waitcnt lgkmcnt(0)
	v_sub_f32_e32 v98, v163, v98
	v_fmac_f32_e32 v98, 0x3e38aa3b, v84
	v_cndmask_b32_e32 v84, v98, v192, vcc
	v_sub_f32_e32 v98, v163, v99
	v_fmac_f32_e32 v98, 0x3e38aa3b, v85
	v_add_u32_e32 v85, 0xffffffa9, v199
	v_cmp_gt_i32_e32 vcc, v85, v166
	s_and_b64 vcc, s[30:31], vcc
	s_nop 0
	v_cndmask_b32_e32 v85, v98, v192, vcc
	v_sub_f32_e32 v98, v163, v100
	v_fmac_f32_e32 v98, 0x3e38aa3b, v86
	v_add_u32_e32 v86, 0xffffffaa, v199
	v_cmp_gt_i32_e32 vcc, v86, v166
	s_and_b64 vcc, s[30:31], vcc
	s_nop 0
	v_cndmask_b32_e32 v86, v98, v192, vcc
	v_sub_f32_e32 v98, v163, v101
	v_fmac_f32_e32 v98, 0x3e38aa3b, v87
	v_add_u32_e32 v87, 0xffffffab, v199
	v_cmp_gt_i32_e32 vcc, v87, v166
	s_and_b64 vcc, s[30:31], vcc
	s_nop 0
	v_cndmask_b32_e32 v87, v98, v192, vcc
	ds_read_b128 v[98:101], v13 offset:43200
	v_cmp_gt_i32_e32 vcc, v102, v166
	s_and_b64 vcc, s[30:31], vcc
	v_add_u32_e32 v102, 0xffffffb8, v199
	s_waitcnt lgkmcnt(0)
	v_sub_f32_e32 v98, v163, v98
	v_fmac_f32_e32 v98, 0x3e38aa3b, v88
	v_cndmask_b32_e32 v88, v98, v192, vcc
	v_sub_f32_e32 v98, v163, v99
	v_fmac_f32_e32 v98, 0x3e38aa3b, v89
	v_add_u32_e32 v89, 0xffffffb1, v199
	v_cmp_gt_i32_e32 vcc, v89, v166
	s_and_b64 vcc, s[30:31], vcc
	s_nop 0
	v_cndmask_b32_e32 v89, v98, v192, vcc
	v_sub_f32_e32 v98, v163, v100
	v_fmac_f32_e32 v98, 0x3e38aa3b, v90
	v_add_u32_e32 v90, 0xffffffb2, v199
	v_cmp_gt_i32_e32 vcc, v90, v166
	s_and_b64 vcc, s[30:31], vcc
	s_nop 0
	v_cndmask_b32_e32 v90, v98, v192, vcc
	v_sub_f32_e32 v98, v163, v101
	v_fmac_f32_e32 v98, 0x3e38aa3b, v91
	v_add_u32_e32 v91, 0xffffffb3, v199
	v_cmp_gt_i32_e32 vcc, v91, v166
	s_and_b64 vcc, s[30:31], vcc
	s_nop 0
	v_cndmask_b32_e32 v91, v98, v192, vcc
	ds_read_b128 v[98:101], v13 offset:43232
	v_cmp_gt_i32_e32 vcc, v102, v166
	s_and_b64 vcc, s[30:31], vcc
	s_waitcnt lgkmcnt(0)
	v_sub_f32_e32 v98, v163, v98
	v_fmac_f32_e32 v98, 0x3e38aa3b, v92
	v_sub_f32_e32 v92, v163, v99
	v_fmac_f32_e32 v92, 0x3e38aa3b, v93
	v_add_u32_e32 v93, 0xffffffb9, v199
	v_cndmask_b32_e32 v98, v98, v192, vcc
	v_cmp_gt_i32_e32 vcc, v93, v166
	s_and_b64 vcc, s[30:31], vcc
	v_add_u32_e32 v93, 0xffffffba, v199
	v_cndmask_b32_e32 v99, v92, v192, vcc
	v_sub_f32_e32 v92, v163, v100
	v_cmp_gt_i32_e32 vcc, v93, v166
	v_fmac_f32_e32 v92, 0x3e38aa3b, v94
	s_and_b64 vcc, s[30:31], vcc
	v_cndmask_b32_e32 v94, v92, v192, vcc
	v_sub_f32_e32 v92, v163, v101
	ds_read_b128 v[100:103], v13 offset:43264
	v_add_u32_e32 v93, 0xffffffbb, v199
	v_cmp_gt_i32_e32 vcc, v93, v166
	v_fmac_f32_e32 v92, 0x3e38aa3b, v95
	s_and_b64 vcc, s[30:31], vcc
	v_subrev_u32_e32 v93, 64, v199
	s_waitcnt lgkmcnt(0)
	v_sub_f32_e32 v95, v163, v100
	v_cndmask_b32_e32 v92, v92, v192, vcc
	v_fmac_f32_e32 v95, 0x3e38aa3b, v64
	v_cmp_gt_i32_e32 vcc, v93, v166
	v_sub_f32_e32 v64, v163, v101
	s_and_b64 vcc, s[30:31], vcc
	v_fmac_f32_e32 v64, 0x3e38aa3b, v65
	v_subrev_u32_e32 v65, 63, v199
	v_cndmask_b32_e32 v93, v95, v192, vcc
	v_cmp_gt_i32_e32 vcc, v65, v166
	s_and_b64 vcc, s[30:31], vcc
	s_nop 0
	v_cndmask_b32_e32 v65, v64, v192, vcc
	v_sub_f32_e32 v64, v163, v102
	v_fmac_f32_e32 v64, 0x3e38aa3b, v66
	v_subrev_u32_e32 v66, 62, v199
	v_cmp_gt_i32_e32 vcc, v66, v166
	s_and_b64 vcc, s[30:31], vcc
	s_nop 0
	v_cndmask_b32_e32 v66, v64, v192, vcc
	v_sub_f32_e32 v64, v163, v103
	ds_read_b128 v[100:103], v13 offset:43296
	v_fmac_f32_e32 v64, 0x3e38aa3b, v67
	v_subrev_u32_e32 v67, 61, v199
	v_cmp_gt_i32_e32 vcc, v67, v166
	s_and_b64 vcc, s[30:31], vcc
	v_subrev_u32_e32 v67, 56, v199
	v_cndmask_b32_e32 v64, v64, v192, vcc
	s_waitcnt lgkmcnt(0)
	v_sub_f32_e32 v95, v163, v100
	v_cmp_gt_i32_e32 vcc, v67, v166
	v_fmac_f32_e32 v95, 0x3e38aa3b, v68
	s_and_b64 vcc, s[30:31], vcc
	v_subrev_u32_e32 v68, 55, v199
	v_cndmask_b32_e32 v100, v95, v192, vcc
	v_sub_f32_e32 v67, v163, v101
	v_cmp_gt_i32_e32 vcc, v68, v166
	v_fmac_f32_e32 v67, 0x3e38aa3b, v69
	s_and_b64 vcc, s[30:31], vcc
	v_subrev_u32_e32 v68, 54, v199
	v_cndmask_b32_e32 v101, v67, v192, vcc
	v_sub_f32_e32 v67, v163, v102
	v_cmp_gt_i32_e32 vcc, v68, v166
	v_fmac_f32_e32 v67, 0x3e38aa3b, v70
	s_and_b64 vcc, s[30:31], vcc
	v_cndmask_b32_e32 v95, v67, v192, vcc
	v_sub_f32_e32 v67, v163, v103
	ds_read_b128 v[102:105], v13 offset:43328
	v_subrev_u32_e32 v68, 53, v199
	v_cmp_gt_i32_e32 vcc, v68, v166
	v_fmac_f32_e32 v67, 0x3e38aa3b, v71
	s_and_b64 vcc, s[30:31], vcc
	v_cndmask_b32_e32 v69, v67, v192, vcc
	v_subrev_u32_e32 v67, 48, v199
	s_waitcnt lgkmcnt(0)
	v_sub_f32_e32 v68, v163, v102
	v_cmp_gt_i32_e32 vcc, v67, v166
	v_fmac_f32_e32 v68, 0x3e38aa3b, v72
	s_and_b64 vcc, s[30:31], vcc
	v_cndmask_b32_e32 v71, v68, v192, vcc
	v_subrev_u32_e32 v68, 47, v199
	v_sub_f32_e32 v67, v163, v103
	v_cmp_gt_i32_e32 vcc, v68, v166
	v_fmac_f32_e32 v67, 0x3e38aa3b, v73
	s_and_b64 vcc, s[30:31], vcc
	v_subrev_u32_e32 v70, 46, v199
	v_cndmask_b32_e32 v67, v67, v192, vcc
	v_sub_f32_e32 v68, v163, v104
	v_cmp_gt_i32_e32 vcc, v70, v166
	v_sub_f32_e32 v70, v163, v105
	ds_read_b128 v[102:105], v13 offset:43360
	v_fmac_f32_e32 v68, 0x3e38aa3b, v74
	s_and_b64 vcc, s[30:31], vcc
	v_subrev_u32_e32 v72, 45, v199
	v_cndmask_b32_e32 v68, v68, v192, vcc
	v_cmp_gt_i32_e32 vcc, v72, v166
	v_fmac_f32_e32 v70, 0x3e38aa3b, v75
	s_and_b64 vcc, s[30:31], vcc
	v_subrev_u32_e32 v72, 40, v199
	v_cndmask_b32_e32 v70, v70, v192, vcc
	s_waitcnt lgkmcnt(0)
	v_sub_f32_e32 v73, v163, v102
	v_cmp_gt_i32_e32 vcc, v72, v166
	v_fmac_f32_e32 v73, 0x3e38aa3b, v76
	s_and_b64 vcc, s[30:31], vcc
	v_cndmask_b32_e32 v75, v73, v192, vcc
	v_subrev_u32_e32 v73, 39, v199
	v_sub_f32_e32 v72, v163, v103
	v_cmp_gt_i32_e32 vcc, v73, v166
	v_fmac_f32_e32 v72, 0x3e38aa3b, v77
	s_and_b64 vcc, s[30:31], vcc
	v_subrev_u32_e32 v73, 38, v199
	v_cndmask_b32_e32 v74, v72, v192, vcc
	v_sub_f32_e32 v72, v163, v104
	v_cmp_gt_i32_e32 vcc, v73, v166
	v_fmac_f32_e32 v72, 0x3e38aa3b, v78
	s_and_b64 vcc, s[30:31], vcc
	v_sub_f32_e32 v73, v163, v105
	v_subrev_u32_e32 v76, 37, v199
	v_cndmask_b32_e32 v72, v72, v192, vcc
	v_fmac_f32_e32 v73, 0x3e38aa3b, v79
	v_cmp_gt_i32_e32 vcc, v76, v166
	ds_read_b128 v[76:79], v13 offset:43392
	s_and_b64 vcc, s[30:31], vcc
	v_subrev_u32_e32 v102, 32, v199
	v_cndmask_b32_e32 v73, v73, v192, vcc
	v_cmp_gt_i32_e32 vcc, v102, v166
	ds_read_b128 v[102:105], v13 offset:43424
	s_waitcnt lgkmcnt(1)
	v_sub_f32_e32 v76, v163, v76
	v_fmac_f32_e32 v76, 0x3e38aa3b, v48
	s_and_b64 vcc, s[30:31], vcc
	v_cndmask_b32_e32 v48, v76, v192, vcc
	v_sub_f32_e32 v76, v163, v77
	v_fmac_f32_e32 v76, 0x3e38aa3b, v49
	v_subrev_u32_e32 v49, 31, v199
	v_cmp_gt_i32_e32 vcc, v49, v166
	v_sub_f32_e32 v49, v163, v78
	s_and_b64 vcc, s[30:31], vcc
	v_fmac_f32_e32 v49, 0x3e38aa3b, v50
	v_subrev_u32_e32 v50, 30, v199
	v_cndmask_b32_e32 v76, v76, v192, vcc
	v_cmp_gt_i32_e32 vcc, v50, v166
	s_and_b64 vcc, s[30:31], vcc
	s_waitcnt lgkmcnt(0)
	v_sub_f32_e32 v77, v163, v102
	v_cndmask_b32_e32 v50, v49, v192, vcc
	v_sub_f32_e32 v49, v163, v79
	v_fmac_f32_e32 v49, 0x3e38aa3b, v51
	v_subrev_u32_e32 v51, 29, v199
	v_cmp_gt_i32_e32 vcc, v51, v166
	s_and_b64 vcc, s[30:31], vcc
	v_subrev_u32_e32 v51, 24, v199
	v_cndmask_b32_e32 v49, v49, v192, vcc
	v_fmac_f32_e32 v77, 0x3e38aa3b, v52
	v_cmp_gt_i32_e32 vcc, v51, v166
	v_sub_f32_e32 v52, v163, v103
	s_and_b64 vcc, s[30:31], vcc
	v_fmac_f32_e32 v52, 0x3e38aa3b, v53
	v_subrev_u32_e32 v53, 23, v199
	v_cndmask_b32_e32 v51, v77, v192, vcc
	v_cmp_gt_i32_e32 vcc, v53, v166
	v_sub_f32_e32 v53, v163, v104
	s_and_b64 vcc, s[30:31], vcc
	v_fmac_f32_e32 v53, 0x3e38aa3b, v54
	v_subrev_u32_e32 v54, 22, v199
	v_cndmask_b32_e32 v52, v52, v192, vcc
	v_cmp_gt_i32_e32 vcc, v54, v166
	v_sub_f32_e32 v54, v163, v105
	ds_read_b128 v[102:105], v13 offset:43456
	s_and_b64 vcc, s[30:31], vcc
	v_fmac_f32_e32 v54, 0x3e38aa3b, v55
	v_subrev_u32_e32 v55, 21, v199
	v_cndmask_b32_e32 v53, v53, v192, vcc
	v_cmp_gt_i32_e32 vcc, v55, v166
	s_and_b64 vcc, s[30:31], vcc
	v_add_u32_e32 v55, -16, v199
	v_cndmask_b32_e32 v54, v54, v192, vcc
	s_waitcnt lgkmcnt(0)
	v_sub_f32_e32 v77, v163, v102
	v_cmp_gt_i32_e32 vcc, v55, v166
	v_fmac_f32_e32 v77, 0x3e38aa3b, v56
	s_and_b64 vcc, s[30:31], vcc
	v_add_u32_e32 v56, -15, v199
	v_cndmask_b32_e32 v77, v77, v192, vcc
	v_sub_f32_e32 v55, v163, v103
	v_cmp_gt_i32_e32 vcc, v56, v166
	v_fmac_f32_e32 v55, 0x3e38aa3b, v57
	s_and_b64 vcc, s[30:31], vcc
	v_add_u32_e32 v56, -14, v199
	v_cndmask_b32_e32 v57, v55, v192, vcc
	v_sub_f32_e32 v55, v163, v104
	v_cmp_gt_i32_e32 vcc, v56, v166
	v_sub_f32_e32 v56, v163, v105
	ds_read_b128 v[102:105], v13 offset:43488
	v_fmac_f32_e32 v55, 0x3e38aa3b, v58
	s_and_b64 vcc, s[30:31], vcc
	v_add_u32_e32 v58, -13, v199
	v_cndmask_b32_e32 v55, v55, v192, vcc
	v_cmp_gt_i32_e32 vcc, v58, v166
	v_fmac_f32_e32 v56, 0x3e38aa3b, v59
	s_and_b64 vcc, s[30:31], vcc
	v_add_u32_e32 v13, -8, v199
	v_cndmask_b32_e32 v56, v56, v192, vcc
	s_waitcnt lgkmcnt(0)
	v_sub_f32_e32 v58, v163, v102
	v_cmp_gt_i32_e32 vcc, v13, v166
	v_fmac_f32_e32 v58, 0x3e38aa3b, v60
	s_and_b64 vcc, s[30:31], vcc
	v_add_u32_e32 v59, -7, v199
	v_cndmask_b32_e32 v13, v58, v192, vcc
	v_sub_f32_e32 v58, v163, v103
	v_cmp_gt_i32_e32 vcc, v59, v166
	v_fmac_f32_e32 v58, 0x3e38aa3b, v61
	s_and_b64 vcc, s[30:31], vcc
	v_add_u32_e32 v60, -6, v199
	v_cndmask_b32_e32 v59, v58, v192, vcc
	v_sub_f32_e32 v58, v163, v104
	v_cmp_gt_i32_e32 vcc, v60, v166
	v_fmac_f32_e32 v58, 0x3e38aa3b, v62
	s_and_b64 vcc, s[30:31], vcc
	v_cndmask_b32_e32 v60, v58, v192, vcc
	v_sub_f32_e32 v58, v163, v105
	v_fmac_f32_e32 v58, 0x3e38aa3b, v63
	v_add_u32_e32 v61, -5, v199
	v_max_f32_e32 v63, v65, v76
	v_cmp_gt_i32_e32 vcc, v61, v166
	v_max_f32_e32 v61, v1, v80
	v_max_f32_e32 v62, v93, v48
	v_max3_f32 v63, v2, v81, v63
	v_max3_f32 v61, v61, v62, v63
	v_max_f32_e32 v62, v66, v50
	v_max_f32_e32 v63, v64, v49
	v_max3_f32 v62, v3, v82, v62
	v_max3_f32 v63, v4, v83, v63
	v_max3_f32 v61, v61, v62, v63
	v_max_f32_e32 v62, v100, v51
	v_max_f32_e32 v63, v101, v52
	v_max3_f32 v62, v5, v84, v62
	v_max3_f32 v63, v6, v85, v63
	v_max3_f32 v61, v61, v62, v63
	v_max_f32_e32 v62, v95, v53
	v_max_f32_e32 v63, v69, v54
	v_max3_f32 v62, v7, v86, v62
	v_max3_f32 v63, v8, v87, v63
	v_max3_f32 v61, v61, v62, v63
	v_max_f32_e32 v62, v71, v77
	v_max_f32_e32 v63, v67, v57
	v_max3_f32 v62, v9, v88, v62
	v_max3_f32 v63, v10, v89, v63
	v_max3_f32 v61, v61, v62, v63
	v_max_f32_e32 v62, v68, v55
	v_max_f32_e32 v63, v70, v56
	v_max3_f32 v62, v11, v90, v62
	v_max3_f32 v63, v12, v91, v63
	s_and_b64 vcc, s[30:31], vcc
	v_max3_f32 v61, v61, v62, v63
	v_max_f32_e32 v62, v75, v13
	v_max_f32_e32 v63, v74, v59
	v_cndmask_b32_e32 v58, v58, v192, vcc
	v_max3_f32 v62, v14, v98, v62
	v_max3_f32 v63, v15, v99, v63
	v_max3_f32 v61, v61, v62, v63
	v_max_f32_e32 v62, v72, v60
	v_max_f32_e32 v63, v73, v58
	v_max3_f32 v62, v96, v94, v62
	v_max3_f32 v63, v97, v92, v63
	v_max3_f32 v61, v61, v62, v63
	v_mov_b32_e32 v62, v61
	s_nop 1
	v_permlane32_swap_b32 v62, v61
	s_nop 1
	s_nop 0
	v_max_f32_e32 v61, v61, v61
	v_max_f32_e32 v62, v62, v62
	v_max_f32_e32 v61, v62, v61
	v_cmp_lt_f32_e32 vcc, s75, v61
	s_or_b64 s[30:31], s[28:29], vcc
	v_cndmask_b32_e64 v62, 0, 1, s[30:31]
	v_cmp_ne_u32_e32 vcc, 0, v62
.Lfox_join_F1:
	s_cbranch_vccz .LBB0_3063
	s_mov_b32 s30, 0x41000000
	v_cmp_lt_f32_e32 vcc, s30, v61
	s_or_b64 vcc, s[28:29], vcc
	s_nop 0
	v_cndmask_b32_e32 v61, 0, v61, vcc
	v_cmp_neq_f32_e32 vcc, 0, v61
	s_cbranch_vccz .LBB0_3062
	v_exp_f32_e64 v62, -v61
	v_sub_f32_e32 v1, v1, v61
	v_sub_f32_e32 v2, v2, v61
	v_sub_f32_e32 v3, v3, v61
	v_cndmask_b32_e64 v62, v62, 0, s[28:29]
	v_pk_mul_f32 v[30:31], v[30:31], v[62:63] op_sel_hi:[1,0]
	v_pk_mul_f32 v[28:29], v[28:29], v[62:63] op_sel_hi:[1,0]
	v_pk_mul_f32 v[26:27], v[26:27], v[62:63] op_sel_hi:[1,0]
	v_pk_mul_f32 v[24:25], v[24:25], v[62:63] op_sel_hi:[1,0]
	v_pk_mul_f32 v[22:23], v[22:23], v[62:63] op_sel_hi:[1,0]
	v_pk_mul_f32 v[20:21], v[20:21], v[62:63] op_sel_hi:[1,0]
	v_pk_mul_f32 v[18:19], v[18:19], v[62:63] op_sel_hi:[1,0]
	v_pk_mul_f32 v[16:17], v[16:17], v[62:63] op_sel_hi:[1,0]
	v_sub_f32_e32 v4, v4, v61
	v_sub_f32_e32 v5, v5, v61
	v_sub_f32_e32 v6, v6, v61
	v_sub_f32_e32 v7, v7, v61
	v_sub_f32_e32 v8, v8, v61
	v_sub_f32_e32 v9, v9, v61
	v_sub_f32_e32 v10, v10, v61
	v_sub_f32_e32 v11, v11, v61
	v_sub_f32_e32 v12, v12, v61
	v_sub_f32_e32 v14, v14, v61
	v_sub_f32_e32 v15, v15, v61
	v_sub_f32_e32 v96, v96, v61
	v_sub_f32_e32 v97, v97, v61
	v_sub_f32_e32 v80, v80, v61
	v_sub_f32_e32 v81, v81, v61
	v_sub_f32_e32 v82, v82, v61
	v_sub_f32_e32 v83, v83, v61
	v_sub_f32_e32 v84, v84, v61
	v_sub_f32_e32 v85, v85, v61
	v_sub_f32_e32 v86, v86, v61
	v_sub_f32_e32 v87, v87, v61
	v_sub_f32_e32 v88, v88, v61
	v_sub_f32_e32 v89, v89, v61
	v_sub_f32_e32 v90, v90, v61
	v_sub_f32_e32 v91, v91, v61
	v_sub_f32_e32 v98, v98, v61
	v_sub_f32_e32 v99, v99, v61
	v_sub_f32_e32 v94, v94, v61
	v_sub_f32_e32 v92, v92, v61
	v_sub_f32_e32 v93, v93, v61
	v_sub_f32_e32 v65, v65, v61
	v_sub_f32_e32 v66, v66, v61
	v_sub_f32_e32 v64, v64, v61
	v_sub_f32_e32 v100, v100, v61
	v_sub_f32_e32 v101, v101, v61
	v_sub_f32_e32 v95, v95, v61
	v_sub_f32_e32 v69, v69, v61
	v_sub_f32_e32 v71, v71, v61
	v_sub_f32_e32 v67, v67, v61
	v_sub_f32_e32 v68, v68, v61
	v_sub_f32_e32 v70, v70, v61
	v_sub_f32_e32 v75, v75, v61
	v_sub_f32_e32 v74, v74, v61
	v_sub_f32_e32 v72, v72, v61
	v_sub_f32_e32 v73, v73, v61
	v_sub_f32_e32 v48, v48, v61
	v_sub_f32_e32 v76, v76, v61
	v_sub_f32_e32 v50, v50, v61
	v_sub_f32_e32 v49, v49, v61
	v_sub_f32_e32 v51, v51, v61
	v_sub_f32_e32 v52, v52, v61
	v_sub_f32_e32 v53, v53, v61
	v_sub_f32_e32 v54, v54, v61
	v_sub_f32_e32 v77, v77, v61
	v_sub_f32_e32 v57, v57, v61
	v_sub_f32_e32 v55, v55, v61
	v_sub_f32_e32 v56, v56, v61
	v_sub_f32_e32 v13, v13, v61
	v_sub_f32_e32 v59, v59, v61
	v_sub_f32_e32 v60, v60, v61
	v_sub_f32_e32 v58, v58, v61
	v_pk_mul_f32 v[46:47], v[46:47], v[62:63] op_sel_hi:[1,0]
	v_pk_mul_f32 v[44:45], v[44:45], v[62:63] op_sel_hi:[1,0]
	v_pk_mul_f32 v[42:43], v[42:43], v[62:63] op_sel_hi:[1,0]
	v_pk_mul_f32 v[40:41], v[40:41], v[62:63] op_sel_hi:[1,0]
	v_pk_mul_f32 v[38:39], v[38:39], v[62:63] op_sel_hi:[1,0]
	v_pk_mul_f32 v[36:37], v[36:37], v[62:63] op_sel_hi:[1,0]
	v_pk_mul_f32 v[34:35], v[34:35], v[62:63] op_sel_hi:[1,0]
	v_pk_mul_f32 v[32:33], v[32:33], v[62:63] op_sel_hi:[1,0]
	v_mul_f32_e32 v195, v195, v62
	v_sub_f32_e32 v163, v163, v61
